# P0 weight transposes for phases P3+ and the pool-weight fold moved out of the prologue: done by the 192 workgroups that idle while 64 run the memory K/V GEMM (hand-written routine, release + counter p
# speedup vs baseline: 1.0578x; 1.0255x over previous
; __global__ void __launch_bounds__(NTHR, 2) hybrid_fwd(Args args) {
;     ...
;         for (int it = gw; it < NIT; it += NGW) {
;             int r = it;
;             if (r < I0) { const int kb = r / 128, nb = r % 128, n0 = 32 * nb; tr_item(w_in, INC, 1024, 64 * kb, n0 < 2048 ? n0 : n0 + 8, W1t, n0, norm_mix_g, 1.0f, scr, lane); continue; } r -= I0;
.LBB0_18:
	s_cmp_lg_u32 s20, 0x100
	s_cbranch_scc1 .Lp0_go
	s_cmp_lt_u32 s70, 2048
	s_cbranch_scc1 .Lp0_go
	s_cmp_lt_u32 s70, 3072
	s_cbranch_scc1 .LBB0_17
	s_cmp_ge_u32 s70, 3584
	s_cbranch_scc1 .LBB0_17

; __global__ void __launch_bounds__(NTHR, 2) hybrid_fwd(Args args) {
;     ...
;         for (int rf_ = 0; rf_ < REP_P0F; ++rf_)
;         for (int bi = blk; bi < 128; bi += G) { const int nb = bi >> 3, kl = bi & 7, k0 = kl * 64 + wave * 8, gb = (k0 >> 7) * 128, n = nb * 64 + lane;
.LBB0_186:
	s_lshl_b32 s75, s74, 3
	s_cmp_eq_u32 s20, 0x100
	s_cbranch_scc1 .LBB0_191
	s_cmpk_gt_i32 s2, 0x7f
	s_cbranch_scc1 .LBB0_191
	s_add_u32 s38, s24, 0x900000
	s_addc_u32 s39, s25, 0
	s_add_u32 s3, s36, 0x7000
	s_addc_u32 s21, s37, 0
	s_lshl_b32 s27, s2, 6
	s_lshl_b32 s29, s20, 6
	s_lshl_b32 s46, s2, 3
	s_lshl_b32 s47, s20, 3
	s_mov_b32 s37, 0
	v_mov_b32_e32 v1, 0
	s_movk_i32 s48, 0xb000
	s_movk_i32 s49, 0xd000
	s_movk_i32 s50, 0xe000
	s_mov_b64 s[40:41], 0x8000
	s_mov_b32 s51, s2

; #define LAS __attribute__((address_space(3)))
; __device__ __forceinline__ void tr_item(const float* W, int ldw, int K, int k0, int sc0, bf16* WT, int dr0, const float* gain, float cs, LAS float* scr, int lane) {
; #pragma unroll 16
;     for (int i = 0; i < 32; ++i) { const int kk = 2 * i + (lane >> 5); const float g = gain ? gain[k0 + kk] * cs : cs;
;         scr[kk * 33 + (lane & 31)] = W[(size_t)(k0 + kk) * ldw + sc0 + (lane & 31)] * g; }
; __global__ void __launch_bounds__(NTHR, 2) hybrid_fwd(Args args) {
;     ...
;             if (r < I0) { const int kb = r / 128, nb = r % 128, n0 = 32 * nb; tr_item(w_in, INC, 1024, 64 * kb, n0 < 2048 ? n0 : n0 + 8, W1t, n0, norm_mix_g, 1.0f, scr, lane); continue; } r -= I0;
;             if (r < I1) { const int kb = r / 32, nb = r % 32; tr_item(w_fox_out, 1024, 1024, 64 * kb, 32 * nb, Wmix + 512, 32 * nb, nullptr, 1.0f, scr, lane); continue; } r -= I1;
;             if (r < I2) { const int kb = r / 32, nb = r % 32; tr_item(w_out, 1024, 1024, 64 * kb, 32 * nb, Wout, 32 * nb, nullptr, 1.0f, scr, lane); continue; } r -= I2;
;             if (r < I3) { const int kb = r / 16, nb = r % 16; tr_item(w_xq, 512, 1024, 64 * kb, 32 * nb, Wxq, 32 * nb, norm_x_g, 0.08838834764831845f * LOG2E, scr, lane); continue; } r -= I3;
;             if (r < I4) { const int kb = r / 32, nb = r % 32; tr_item(w_xkv, 1024, 1024, 64 * kb, 32 * nb, Wxkv, 32 * nb, norm_mem_g, 1.0f, scr, lane); continue; } r -= I4;
;             if (r < I5) { const int kb = r / 32, nb = r % 32; tr_item(w_xo, 1024, 512, 64 * kb, 32 * nb, Wxo, 32 * nb, nullptr, 1.0f, scr, lane); continue; } r -= I5;
;             if (r < I6) { const int kb = r / 176, nb = r % 176, n0 = 32 * nb, j = n0 >> 8, wi = n0 & 255; const int sc = wi < 128 ? 128 * j + wi : DFF + 128 * j + (wi - 128);
;                           tr_item(w_ffn_in, 2 * DFF, 1024, 64 * kb, sc, Wffi, n0, norm_ffn_g, 1.0f, scr, lane); continue; } r -= I6;
;             { const int kb = r / 32, nb = r % 32; tr_item(w_ffn_out, 1024, DFF, 64 * kb, 32 * nb, Wffo, 32 * nb, nullptr, 1.0f, scr, lane); }
.LBB0_349:
	s_cmp_lg_u32 s20, 0x100
	s_cbranch_scc1 .Ldef_skip
	s_cmp_lt_u32 s2, 64
	s_cbranch_scc1 .Ldef_skip
	v_lshrrev_b32_e32 v80, 5, v212
	v_and_b32_e32 v81, 31, v212
	v_lshlrev_b32_e32 v81, 2, v81
	v_and_b32_e32 v82, 7, v212
	v_lshlrev_b32_e32 v82, 4, v82
	v_lshrrev_b32_e32 v83, 3, v212
	v_lshlrev_b32_e32 v85, 2, v80
	s_lshl_b32 s79, s74, 14
	v_mul_u32_u24_e32 v86, 0x84, v80
	v_add3_u32 v86, v86, v81, s79
	v_and_b32_e32 v87, 7, v212
	v_mul_u32_u24_e32 v87, 0x420, v87
	v_lshl_add_u32 v87, v83, 2, v87
	v_add_u32_e32 v87, s79, v87
	s_sub_i32 s78, s2, 64
	s_lshl_b32 s78, s78, 3
	s_add_i32 s78, s78, s74
	s_mov_b32 s77, s78
.Ldef_item:
	s_cmp_ge_u32 s77, 5504
	s_cbranch_scc1 .Ldef_items_done
	s_cmp_ge_u32 s77, 256
	s_cbranch_scc1 .Ldef_m1
	s_sub_i32 s24, s77, 0
	s_load_dwordx2 s[8:9], s[0:1], 0x48
	s_mov_b32 s32, 0
	s_mov_b32 s14, 0x1000
	s_mov_b32 s30, 0x800
	s_mov_b32 s31, 0x3f800000
	s_add_u32 s12, s18, 0x900400
	s_addc_u32 s13, s19, 0
	s_lshr_b32 s25, s24, 5
	s_and_b32 s26, s24, 31
	s_lshl_b32 s27, s25, 6
	s_lshl_b32 s28, s26, 5
	s_mov_b32 s29, s28
	s_branch .Ldef_decoded
.Ldef_m1:
	s_cmp_ge_u32 s77, 768
	s_cbranch_scc1 .Ldef_m2
	s_sub_i32 s24, s77, 256
	s_load_dwordx2 s[8:9], s[0:1], 0x50
	s_mov_b32 s32, 0
	s_mov_b32 s14, 0x1000
	s_mov_b32 s30, 0x800
	s_mov_b32 s31, 0x3f800000
	s_add_u32 s12, s18, 0xb00000
	s_addc_u32 s13, s19, 0
	s_lshr_b32 s25, s24, 5
	s_and_b32 s26, s24, 31
	s_lshl_b32 s27, s25, 6
	s_lshl_b32 s28, s26, 5
	s_mov_b32 s29, s28
	s_branch .Ldef_decoded
.Ldef_m2:
	s_cmp_ge_u32 s77, 1024
	s_cbranch_scc1 .Ldef_m3
	s_sub_i32 s24, s77, 768
	s_load_dwordx2 s[8:9], s[0:1], 0x68
	s_load_dwordx2 s[10:11], s[0:1], 0x58
	s_mov_b32 s32, 1
	s_mov_b32 s14, 0x800
	s_mov_b32 s30, 0x800
	s_mov_b32 s31, 0x3e0293ee
	s_add_u32 s12, s18, 0xd00000
	s_addc_u32 s13, s19, 0
	s_lshr_b32 s25, s24, 4
	s_and_b32 s26, s24, 15
	s_lshl_b32 s27, s25, 6
	s_lshl_b32 s28, s26, 5
	s_mov_b32 s29, s28
	s_branch .Ldef_decoded
.Ldef_m3:
	s_cmp_ge_u32 s77, 1280
	s_cbranch_scc1 .Ldef_m4
	s_sub_i32 s24, s77, 1024
	s_load_dwordx2 s[8:9], s[0:1], 0x78
	s_mov_b32 s32, 0
	s_mov_b32 s14, 0x1000
	s_mov_b32 s30, 0x400
	s_mov_b32 s31, 0x3f800000
	s_add_u32 s12, s18, 0x1000000
	s_addc_u32 s13, s19, 0
	s_lshr_b32 s25, s24, 5
	s_and_b32 s26, s24, 31
	s_lshl_b32 s27, s25, 6
	s_lshl_b32 s28, s26, 5
	s_mov_b32 s29, s28
	s_branch .Ldef_decoded
.Ldef_m4:
	s_cmp_ge_u32 s77, 4096
	s_cbranch_scc1 .Ldef_m5
	s_sub_i32 s24, s77, 1280
	s_load_dwordx2 s[8:9], s[0:1], 0x88
	s_load_dwordx2 s[10:11], s[0:1], 0x80
	s_mov_b32 s32, 1
	s_mov_b32 s14, 0x5800
	s_mov_b32 s30, 0x800
	s_mov_b32 s31, 0x3f800000
	s_add_u32 s12, s18, 0x1100000
	s_addc_u32 s13, s19, 0
	s_mul_i32 s25, s24, 0x1746
	s_lshr_b32 s25, s25, 20
	s_mul_i32 s26, s25, 176
	s_sub_i32 s26, s24, s26
	s_lshl_b32 s27, s25, 6
	s_lshl_b32 s28, s26, 5
	s_lshr_b32 s29, s28, 8
	s_lshl_b32 s29, s29, 7
	s_and_b32 s79, s28, 255
	s_add_i32 s29, s29, s79
	s_cmp_ge_u32 s79, 128
	s_cselect_b32 s79, 2688, 0
	s_add_i32 s29, s29, s79
	s_branch .Ldef_decoded
.Ldef_m5:
	s_sub_i32 s24, s77, 4096
	s_load_dwordx2 s[8:9], s[0:1], 0x90
	s_mov_b32 s32, 0
	s_mov_b32 s14, 0x1000
	s_mov_b32 s30, 0x1600
	s_mov_b32 s31, 0x3f800000
	s_add_u32 s12, s18, 0x1c00000
	s_addc_u32 s13, s19, 0
	s_lshr_b32 s25, s24, 5
	s_and_b32 s26, s24, 31
	s_lshl_b32 s27, s25, 6
	s_lshl_b32 s28, s26, 5
	s_mov_b32 s29, s28
.Ldef_decoded:
	s_waitcnt lgkmcnt(0)
	s_mul_i32 s79, s27, s14
	s_lshl_b32 s88, s29, 2
	s_add_u32 s79, s79, s88
	s_add_u32 s82, s8, s79
	s_addc_u32 s83, s9, 0
	s_lshl_b32 s89, s14, 1
	v_mad_u32_u24 v84, v80, s14, v81
	global_load_dword v0, v84, s[82:83] nt
	s_add_u32 s82, s82, s89
	s_addc_u32 s83, s83, 0
	global_load_dword v1, v84, s[82:83] nt
	s_add_u32 s82, s82, s89
	s_addc_u32 s83, s83, 0
	global_load_dword v2, v84, s[82:83] nt
	s_add_u32 s82, s82, s89
	s_addc_u32 s83, s83, 0
	global_load_dword v3, v84, s[82:83] nt
	s_add_u32 s82, s82, s89
	s_addc_u32 s83, s83, 0
	global_load_dword v4, v84, s[82:83] nt
	s_add_u32 s82, s82, s89
	s_addc_u32 s83, s83, 0
	global_load_dword v5, v84, s[82:83] nt
	s_add_u32 s82, s82, s89
	s_addc_u32 s83, s83, 0
	global_load_dword v6, v84, s[82:83] nt
	s_add_u32 s82, s82, s89
	s_addc_u32 s83, s83, 0
	global_load_dword v7, v84, s[82:83] nt
	s_add_u32 s82, s82, s89
	s_addc_u32 s83, s83, 0
	global_load_dword v8, v84, s[82:83] nt
	s_add_u32 s82, s82, s89
	s_addc_u32 s83, s83, 0
	global_load_dword v9, v84, s[82:83] nt
	s_add_u32 s82, s82, s89
	s_addc_u32 s83, s83, 0
	global_load_dword v10, v84, s[82:83] nt
	s_add_u32 s82, s82, s89
	s_addc_u32 s83, s83, 0
	global_load_dword v11, v84, s[82:83] nt
	s_add_u32 s82, s82, s89
	s_addc_u32 s83, s83, 0
	global_load_dword v12, v84, s[82:83] nt
	s_add_u32 s82, s82, s89
	s_addc_u32 s83, s83, 0
	global_load_dword v13, v84, s[82:83] nt
	s_add_u32 s82, s82, s89
	s_addc_u32 s83, s83, 0
	global_load_dword v14, v84, s[82:83] nt
	s_add_u32 s82, s82, s89
	s_addc_u32 s83, s83, 0
	global_load_dword v15, v84, s[82:83] nt
	s_add_u32 s82, s82, s89
	s_addc_u32 s83, s83, 0
	global_load_dword v16, v84, s[82:83] nt
	s_add_u32 s82, s82, s89
	s_addc_u32 s83, s83, 0
	global_load_dword v17, v84, s[82:83] nt
	s_add_u32 s82, s82, s89
	s_addc_u32 s83, s83, 0
	global_load_dword v18, v84, s[82:83] nt
	s_add_u32 s82, s82, s89
	s_addc_u32 s83, s83, 0
	global_load_dword v19, v84, s[82:83] nt
	s_add_u32 s82, s82, s89
	s_addc_u32 s83, s83, 0
	global_load_dword v20, v84, s[82:83] nt
	s_add_u32 s82, s82, s89
	s_addc_u32 s83, s83, 0
	global_load_dword v21, v84, s[82:83] nt
	s_add_u32 s82, s82, s89
	s_addc_u32 s83, s83, 0
	global_load_dword v22, v84, s[82:83] nt
	s_add_u32 s82, s82, s89
	s_addc_u32 s83, s83, 0
	global_load_dword v23, v84, s[82:83] nt
	s_add_u32 s82, s82, s89
	s_addc_u32 s83, s83, 0
	global_load_dword v24, v84, s[82:83] nt
	s_add_u32 s82, s82, s89
	s_addc_u32 s83, s83, 0
	global_load_dword v25, v84, s[82:83] nt
	s_add_u32 s82, s82, s89
	s_addc_u32 s83, s83, 0
	global_load_dword v26, v84, s[82:83] nt
	s_add_u32 s82, s82, s89
	s_addc_u32 s83, s83, 0
	global_load_dword v27, v84, s[82:83] nt
	s_add_u32 s82, s82, s89
	s_addc_u32 s83, s83, 0
	global_load_dword v28, v84, s[82:83] nt
	s_add_u32 s82, s82, s89
	s_addc_u32 s83, s83, 0
	global_load_dword v29, v84, s[82:83] nt
	s_add_u32 s82, s82, s89
	s_addc_u32 s83, s83, 0
	global_load_dword v30, v84, s[82:83] nt
	s_add_u32 s82, s82, s89
	s_addc_u32 s83, s83, 0
	global_load_dword v31, v84, s[82:83] nt
	s_cmp_eq_u32 s32, 0
	s_cbranch_scc1 .Ldef_nogain
; __device__ __forceinline__ void tr_item(const float* W, int ldw, int K, int k0, int sc0, bf16* WT, int dr0, const float* gain, float cs, LAS float* scr, int lane) {
;     ...
;     for (int i = 0; i < 32; ++i) { const int kk = 2 * i + (lane >> 5); const float g = gain ? gain[k0 + kk] * cs : cs;
;         scr[kk * 33 + (lane & 31)] = W[(size_t)(k0 + kk) * ldw + sc0 + (lane & 31)] * g; }
;     asm volatile("s_waitcnt lgkmcnt(0)" ::: "memory");
	s_lshl_b32 s79, s27, 2
	s_add_u32 s84, s10, s79
	s_addc_u32 s85, s11, 0
	global_load_dword v32, v85, s[84:85] offset:0
	global_load_dword v33, v85, s[84:85] offset:8
	global_load_dword v34, v85, s[84:85] offset:16
	global_load_dword v35, v85, s[84:85] offset:24
	global_load_dword v36, v85, s[84:85] offset:32
	global_load_dword v37, v85, s[84:85] offset:40
	global_load_dword v38, v85, s[84:85] offset:48
	global_load_dword v39, v85, s[84:85] offset:56
	global_load_dword v40, v85, s[84:85] offset:64
	global_load_dword v41, v85, s[84:85] offset:72
	global_load_dword v42, v85, s[84:85] offset:80
	global_load_dword v43, v85, s[84:85] offset:88
	global_load_dword v44, v85, s[84:85] offset:96
	global_load_dword v45, v85, s[84:85] offset:104
	global_load_dword v46, v85, s[84:85] offset:112
	global_load_dword v47, v85, s[84:85] offset:120
	global_load_dword v48, v85, s[84:85] offset:128
	global_load_dword v49, v85, s[84:85] offset:136
	global_load_dword v50, v85, s[84:85] offset:144
	global_load_dword v51, v85, s[84:85] offset:152
	global_load_dword v52, v85, s[84:85] offset:160
	global_load_dword v53, v85, s[84:85] offset:168
	global_load_dword v54, v85, s[84:85] offset:176
	global_load_dword v55, v85, s[84:85] offset:184
	global_load_dword v56, v85, s[84:85] offset:192
	global_load_dword v57, v85, s[84:85] offset:200
	global_load_dword v58, v85, s[84:85] offset:208
	global_load_dword v59, v85, s[84:85] offset:216
	global_load_dword v60, v85, s[84:85] offset:224
	global_load_dword v61, v85, s[84:85] offset:232
	global_load_dword v62, v85, s[84:85] offset:240
	global_load_dword v63, v85, s[84:85] offset:248
	s_waitcnt vmcnt(0)
	v_mul_f32_e32 v32, s31, v32
	v_mul_f32_e32 v33, s31, v33
	v_mul_f32_e32 v34, s31, v34
	v_mul_f32_e32 v35, s31, v35
	v_mul_f32_e32 v36, s31, v36
	v_mul_f32_e32 v37, s31, v37
	v_mul_f32_e32 v38, s31, v38
	v_mul_f32_e32 v39, s31, v39
	v_mul_f32_e32 v40, s31, v40
	v_mul_f32_e32 v41, s31, v41
	v_mul_f32_e32 v42, s31, v42
	v_mul_f32_e32 v43, s31, v43
	v_mul_f32_e32 v44, s31, v44
	v_mul_f32_e32 v45, s31, v45
	v_mul_f32_e32 v46, s31, v46
	v_mul_f32_e32 v47, s31, v47
	v_mul_f32_e32 v48, s31, v48
	v_mul_f32_e32 v49, s31, v49
	v_mul_f32_e32 v50, s31, v50
	v_mul_f32_e32 v51, s31, v51
	v_mul_f32_e32 v52, s31, v52
	v_mul_f32_e32 v53, s31, v53
	v_mul_f32_e32 v54, s31, v54
	v_mul_f32_e32 v55, s31, v55
	v_mul_f32_e32 v56, s31, v56
	v_mul_f32_e32 v57, s31, v57
	v_mul_f32_e32 v58, s31, v58
	v_mul_f32_e32 v59, s31, v59
	v_mul_f32_e32 v60, s31, v60
	v_mul_f32_e32 v61, s31, v61
	v_mul_f32_e32 v62, s31, v62
	v_mul_f32_e32 v63, s31, v63
	s_branch .Ldef_scale
.Ldef_nogain:
	v_mov_b32_e32 v32, s31
	v_mov_b32_e32 v33, s31
	v_mov_b32_e32 v34, s31
	v_mov_b32_e32 v35, s31
	v_mov_b32_e32 v36, s31
	v_mov_b32_e32 v37, s31
	v_mov_b32_e32 v38, s31
	v_mov_b32_e32 v39, s31
	v_mov_b32_e32 v40, s31
	v_mov_b32_e32 v41, s31
	v_mov_b32_e32 v42, s31
	v_mov_b32_e32 v43, s31
	v_mov_b32_e32 v44, s31
	v_mov_b32_e32 v45, s31
	v_mov_b32_e32 v46, s31
	v_mov_b32_e32 v47, s31
	v_mov_b32_e32 v48, s31
	v_mov_b32_e32 v49, s31
	v_mov_b32_e32 v50, s31
	v_mov_b32_e32 v51, s31
	v_mov_b32_e32 v52, s31
	v_mov_b32_e32 v53, s31
	v_mov_b32_e32 v54, s31
	v_mov_b32_e32 v55, s31
	v_mov_b32_e32 v56, s31
	v_mov_b32_e32 v57, s31
	v_mov_b32_e32 v58, s31
	v_mov_b32_e32 v59, s31
	v_mov_b32_e32 v60, s31
	v_mov_b32_e32 v61, s31
	v_mov_b32_e32 v62, s31
	v_mov_b32_e32 v63, s31
	s_waitcnt vmcnt(0)
.Ldef_scale:
	v_mul_f32_e32 v0, v0, v32
	v_mul_f32_e32 v1, v1, v33
	v_mul_f32_e32 v2, v2, v34
	v_mul_f32_e32 v3, v3, v35
	v_mul_f32_e32 v4, v4, v36
	v_mul_f32_e32 v5, v5, v37
	v_mul_f32_e32 v6, v6, v38
	v_mul_f32_e32 v7, v7, v39
	v_mul_f32_e32 v8, v8, v40
	v_mul_f32_e32 v9, v9, v41
	v_mul_f32_e32 v10, v10, v42
	v_mul_f32_e32 v11, v11, v43
	v_mul_f32_e32 v12, v12, v44
	v_mul_f32_e32 v13, v13, v45
	v_mul_f32_e32 v14, v14, v46
	v_mul_f32_e32 v15, v15, v47
	v_mul_f32_e32 v16, v16, v48
	v_mul_f32_e32 v17, v17, v49
	v_mul_f32_e32 v18, v18, v50
	v_mul_f32_e32 v19, v19, v51
	v_mul_f32_e32 v20, v20, v52
	v_mul_f32_e32 v21, v21, v53
	v_mul_f32_e32 v22, v22, v54
	v_mul_f32_e32 v23, v23, v55
	v_mul_f32_e32 v24, v24, v56
	v_mul_f32_e32 v25, v25, v57
	v_mul_f32_e32 v26, v26, v58
	v_mul_f32_e32 v27, v27, v59
	v_mul_f32_e32 v28, v28, v60
	v_mul_f32_e32 v29, v29, v61
	v_mul_f32_e32 v30, v30, v62
	v_mul_f32_e32 v31, v31, v63
	ds_write_b32 v86, v0 offset:0
	ds_write_b32 v86, v1 offset:264
	ds_write_b32 v86, v2 offset:528
	ds_write_b32 v86, v3 offset:792
	ds_write_b32 v86, v4 offset:1056
	ds_write_b32 v86, v5 offset:1320
	ds_write_b32 v86, v6 offset:1584
	ds_write_b32 v86, v7 offset:1848
	ds_write_b32 v86, v8 offset:2112
	ds_write_b32 v86, v9 offset:2376
	ds_write_b32 v86, v10 offset:2640
	ds_write_b32 v86, v11 offset:2904
	ds_write_b32 v86, v12 offset:3168
	ds_write_b32 v86, v13 offset:3432
	ds_write_b32 v86, v14 offset:3696
	ds_write_b32 v86, v15 offset:3960
	ds_write_b32 v86, v16 offset:4224
	ds_write_b32 v86, v17 offset:4488
	ds_write_b32 v86, v18 offset:4752
	ds_write_b32 v86, v19 offset:5016
	ds_write_b32 v86, v20 offset:5280
	ds_write_b32 v86, v21 offset:5544
	ds_write_b32 v86, v22 offset:5808
	ds_write_b32 v86, v23 offset:6072
	ds_write_b32 v86, v24 offset:6336
	ds_write_b32 v86, v25 offset:6600
	ds_write_b32 v86, v26 offset:6864
	ds_write_b32 v86, v27 offset:7128
	ds_write_b32 v86, v28 offset:7392
	ds_write_b32 v86, v29 offset:7656
	ds_write_b32 v86, v30 offset:7920
	ds_write_b32 v86, v31 offset:8184
	s_waitcnt lgkmcnt(0)
; #define LAS __attribute__((address_space(3)))
; __device__ __forceinline__ unsigned pk2(float lo, float hi) { return pg8::cvt_pk_bf16(lo, hi); }
; __device__ __forceinline__ void tr_item(const float* W, int ldw, int K, int k0, int sc0, bf16* WT, int dr0, const float* gain, float cs, LAS float* scr, int lane) {
;     ...
;     for (int j = 0; j < 4; ++j) { const int n = (lane >> 3) + 8 * j; const LAS float* s = scr + (8 * c) * 33 + n;
;         u32x4 o; o.x = pk2(s[0 * 33], s[1 * 33]); o.y = pk2(s[2 * 33], s[3 * 33]); o.z = pk2(s[4 * 33], s[5 * 33]); o.w = pk2(s[6 * 33], s[7 * 33]);
;         *(u32x4*)(WT + (size_t)(dr0 + n) * K + k0 + 8 * c) = o; }
;     asm volatile("s_waitcnt lgkmcnt(0)" ::: "memory");
; __global__ void __launch_bounds__(NTHR, 2) hybrid_fwd(Args args) {
;     ...
;         for (int bi = blk; bi < 128; bi += G) { const int nb = bi >> 3, kl = bi & 7, k0 = kl * 64 + wave * 8, gb = (k0 >> 7) * 128, n = nb * 64 + lane;
;             float a[8];
; #pragma unroll
;             for (int kk = 0; kk < 8; ++kk) a[kk] = 0.f;
; #pragma unroll 8
;             for (int d = 0; d < 128; ++d) { const float wv = w_pool_out[(size_t)(gb + d) * 1024 + n] * pool_scale[gb + d];
	s_mul_i32 s79, s28, s30
	s_lshl_b32 s88, s27, 1
	s_add_u32 s79, s79, s88
	s_add_u32 s86, s12, s79
	s_addc_u32 s87, s13, 0
	s_lshl_b32 s89, s30, 3
	v_mad_u32_u24 v88, v83, s30, v82
	ds_read2_b32 v[64:65], v87 offset0:0 offset1:33
	ds_read2_b32 v[66:67], v87 offset0:66 offset1:99
	ds_read2_b32 v[68:69], v87 offset0:132 offset1:165
	ds_read2_b32 v[70:71], v87 offset0:198 offset1:231
	s_waitcnt lgkmcnt(0)
	v_cvt_pk_bf16_f32 v72, v64, v65
	v_cvt_pk_bf16_f32 v73, v66, v67
	v_cvt_pk_bf16_f32 v74, v68, v69
	v_cvt_pk_bf16_f32 v75, v70, v71
	global_store_dwordx4 v88, v[72:75], s[86:87]
	s_add_u32 s86, s86, s89
	s_addc_u32 s87, s87, 0
	s_nop 1
	ds_read2_b32 v[64:65], v87 offset0:8 offset1:41
	ds_read2_b32 v[66:67], v87 offset0:74 offset1:107
	ds_read2_b32 v[68:69], v87 offset0:140 offset1:173
	ds_read2_b32 v[70:71], v87 offset0:206 offset1:239
	s_waitcnt lgkmcnt(0)
	v_cvt_pk_bf16_f32 v72, v64, v65
	v_cvt_pk_bf16_f32 v73, v66, v67
	v_cvt_pk_bf16_f32 v74, v68, v69
	v_cvt_pk_bf16_f32 v75, v70, v71
	global_store_dwordx4 v88, v[72:75], s[86:87]
	s_add_u32 s86, s86, s89
	s_addc_u32 s87, s87, 0
	s_nop 1
	ds_read2_b32 v[64:65], v87 offset0:16 offset1:49
	ds_read2_b32 v[66:67], v87 offset0:82 offset1:115
	ds_read2_b32 v[68:69], v87 offset0:148 offset1:181
	ds_read2_b32 v[70:71], v87 offset0:214 offset1:247
	s_waitcnt lgkmcnt(0)
	v_cvt_pk_bf16_f32 v72, v64, v65
	v_cvt_pk_bf16_f32 v73, v66, v67
	v_cvt_pk_bf16_f32 v74, v68, v69
	v_cvt_pk_bf16_f32 v75, v70, v71
	global_store_dwordx4 v88, v[72:75], s[86:87]
	s_add_u32 s86, s86, s89
	s_addc_u32 s87, s87, 0
	s_nop 1
	ds_read2_b32 v[64:65], v87 offset0:24 offset1:57
	ds_read2_b32 v[66:67], v87 offset0:90 offset1:123
	ds_read2_b32 v[68:69], v87 offset0:156 offset1:189
	ds_read2_b32 v[70:71], v87 offset0:222 offset1:255
	s_waitcnt lgkmcnt(0)
	v_cvt_pk_bf16_f32 v72, v64, v65
	v_cvt_pk_bf16_f32 v73, v66, v67
	v_cvt_pk_bf16_f32 v74, v68, v69
	v_cvt_pk_bf16_f32 v75, v70, v71
	global_store_dwordx4 v88, v[72:75], s[86:87]
	s_waitcnt lgkmcnt(0)
	s_addk_i32 s77, 0x600
	s_branch .Ldef_item
.Ldef_items_done:
	s_cmp_ge_u32 s2, 192
	s_cbranch_scc1 .Ldef_fold_done
	s_load_dwordx2 s[8:9], s[0:1], 0x30
	s_load_dwordx2 s[10:11], s[0:1], 0x38
	s_load_dwordx2 s[12:13], s[0:1], 0x40
	s_sub_i32 s24, s2, 64
	s_lshr_b32 s25, s24, 3
	s_and_b32 s26, s24, 7
	s_lshl_b32 s27, s26, 6
	s_lshl_b32 s79, s74, 3
	s_add_i32 s27, s27, s79
	s_and_b32 s28, s27, 0xffffff80
	s_lshl_b32 s29, s25, 6
	v_add_u32_e32 v155, s29, v212
	v_lshlrev_b32_e32 v156, 2, v155
	v_lshlrev_b32_e32 v157, 2, v212
	s_waitcnt lgkmcnt(0)
	s_lshl_b32 s79, s28, 12
	s_add_u32 s82, s12, s79
	s_addc_u32 s83, s13, 0
	global_load_dword v0, v156, s[82:83] nt
	s_add_u32 s82, s82, 0x1000
	s_addc_u32 s83, s83, 0
	global_load_dword v1, v156, s[82:83] nt
	s_add_u32 s82, s82, 0x1000
	s_addc_u32 s83, s83, 0
	global_load_dword v2, v156, s[82:83] nt
	s_add_u32 s82, s82, 0x1000
	s_addc_u32 s83, s83, 0
	global_load_dword v3, v156, s[82:83] nt
	s_add_u32 s82, s82, 0x1000
	s_addc_u32 s83, s83, 0
	global_load_dword v4, v156, s[82:83] nt
	s_add_u32 s82, s82, 0x1000
	s_addc_u32 s83, s83, 0
	global_load_dword v5, v156, s[82:83] nt
	s_add_u32 s82, s82, 0x1000
	s_addc_u32 s83, s83, 0
	global_load_dword v6, v156, s[82:83] nt
	s_add_u32 s82, s82, 0x1000
	s_addc_u32 s83, s83, 0
	global_load_dword v7, v156, s[82:83] nt
	s_add_u32 s82, s82, 0x1000
	s_addc_u32 s83, s83, 0
	global_load_dword v8, v156, s[82:83] nt
	s_add_u32 s82, s82, 0x1000
	s_addc_u32 s83, s83, 0
	global_load_dword v9, v156, s[82:83] nt
	s_add_u32 s82, s82, 0x1000
	s_addc_u32 s83, s83, 0
	global_load_dword v10, v156, s[82:83] nt
	s_add_u32 s82, s82, 0x1000
	s_addc_u32 s83, s83, 0
	global_load_dword v11, v156, s[82:83] nt
	s_add_u32 s82, s82, 0x1000
	s_addc_u32 s83, s83, 0
	global_load_dword v12, v156, s[82:83] nt
	s_add_u32 s82, s82, 0x1000
	s_addc_u32 s83, s83, 0
	global_load_dword v13, v156, s[82:83] nt
	s_add_u32 s82, s82, 0x1000
	s_addc_u32 s83, s83, 0
	global_load_dword v14, v156, s[82:83] nt
	s_add_u32 s82, s82, 0x1000
	s_addc_u32 s83, s83, 0
	global_load_dword v15, v156, s[82:83] nt
	s_add_u32 s82, s82, 0x1000
	s_addc_u32 s83, s83, 0
	global_load_dword v16, v156, s[82:83] nt
	s_add_u32 s82, s82, 0x1000
	s_addc_u32 s83, s83, 0
	global_load_dword v17, v156, s[82:83] nt
	s_add_u32 s82, s82, 0x1000
	s_addc_u32 s83, s83, 0
	global_load_dword v18, v156, s[82:83] nt
	s_add_u32 s82, s82, 0x1000
	s_addc_u32 s83, s83, 0
	global_load_dword v19, v156, s[82:83] nt
	s_add_u32 s82, s82, 0x1000
	s_addc_u32 s83, s83, 0
	global_load_dword v20, v156, s[82:83] nt
	s_add_u32 s82, s82, 0x1000
	s_addc_u32 s83, s83, 0
	global_load_dword v21, v156, s[82:83] nt
	s_add_u32 s82, s82, 0x1000
	s_addc_u32 s83, s83, 0
	global_load_dword v22, v156, s[82:83] nt
	s_add_u32 s82, s82, 0x1000
	s_addc_u32 s83, s83, 0
	global_load_dword v23, v156, s[82:83] nt
	s_add_u32 s82, s82, 0x1000
	s_addc_u32 s83, s83, 0
	global_load_dword v24, v156, s[82:83] nt
	s_add_u32 s82, s82, 0x1000
	s_addc_u32 s83, s83, 0
	global_load_dword v25, v156, s[82:83] nt
	s_add_u32 s82, s82, 0x1000
	s_addc_u32 s83, s83, 0
	global_load_dword v26, v156, s[82:83] nt
	s_add_u32 s82, s82, 0x1000
	s_addc_u32 s83, s83, 0
	global_load_dword v27, v156, s[82:83] nt
	s_add_u32 s82, s82, 0x1000
	s_addc_u32 s83, s83, 0
	global_load_dword v28, v156, s[82:83] nt
	s_add_u32 s82, s82, 0x1000
	s_addc_u32 s83, s83, 0
	global_load_dword v29, v156, s[82:83] nt
	s_add_u32 s82, s82, 0x1000
	s_addc_u32 s83, s83, 0
	global_load_dword v30, v156, s[82:83] nt
	s_add_u32 s82, s82, 0x1000
	s_addc_u32 s83, s83, 0
	global_load_dword v31, v156, s[82:83] nt
	s_add_u32 s82, s82, 0x1000
	s_addc_u32 s83, s83, 0
	global_load_dword v32, v156, s[82:83] nt
; __global__ void __launch_bounds__(NTHR, 2) hybrid_fwd(Args args) {
;     ...
; #pragma unroll 8
;             for (int d = 0; d < 128; ++d) { const float wv = w_pool_out[(size_t)(gb + d) * 1024 + n] * pool_scale[gb + d];
	s_add_u32 s82, s82, 0x1000
	s_addc_u32 s83, s83, 0
	global_load_dword v33, v156, s[82:83] nt
	s_add_u32 s82, s82, 0x1000
	s_addc_u32 s83, s83, 0
	global_load_dword v34, v156, s[82:83] nt
	s_add_u32 s82, s82, 0x1000
	s_addc_u32 s83, s83, 0
	global_load_dword v35, v156, s[82:83] nt
	s_add_u32 s82, s82, 0x1000
	s_addc_u32 s83, s83, 0
	global_load_dword v36, v156, s[82:83] nt
	s_add_u32 s82, s82, 0x1000
	s_addc_u32 s83, s83, 0
	global_load_dword v37, v156, s[82:83] nt
	s_add_u32 s82, s82, 0x1000
	s_addc_u32 s83, s83, 0
	global_load_dword v38, v156, s[82:83] nt
	s_add_u32 s82, s82, 0x1000
	s_addc_u32 s83, s83, 0
	global_load_dword v39, v156, s[82:83] nt
	s_add_u32 s82, s82, 0x1000
	s_addc_u32 s83, s83, 0
	global_load_dword v40, v156, s[82:83] nt
	s_add_u32 s82, s82, 0x1000
	s_addc_u32 s83, s83, 0
	global_load_dword v41, v156, s[82:83] nt
	s_add_u32 s82, s82, 0x1000
	s_addc_u32 s83, s83, 0
	global_load_dword v42, v156, s[82:83] nt
	s_add_u32 s82, s82, 0x1000
	s_addc_u32 s83, s83, 0
	global_load_dword v43, v156, s[82:83] nt
	s_add_u32 s82, s82, 0x1000
	s_addc_u32 s83, s83, 0
	global_load_dword v44, v156, s[82:83] nt
	s_add_u32 s82, s82, 0x1000
	s_addc_u32 s83, s83, 0
	global_load_dword v45, v156, s[82:83] nt
	s_add_u32 s82, s82, 0x1000
	s_addc_u32 s83, s83, 0
	global_load_dword v46, v156, s[82:83] nt
	s_add_u32 s82, s82, 0x1000
	s_addc_u32 s83, s83, 0
	global_load_dword v47, v156, s[82:83] nt
	s_add_u32 s82, s82, 0x1000
	s_addc_u32 s83, s83, 0
	global_load_dword v48, v156, s[82:83] nt
	s_add_u32 s82, s82, 0x1000
	s_addc_u32 s83, s83, 0
	global_load_dword v49, v156, s[82:83] nt
	s_add_u32 s82, s82, 0x1000
	s_addc_u32 s83, s83, 0
	global_load_dword v50, v156, s[82:83] nt
	s_add_u32 s82, s82, 0x1000
	s_addc_u32 s83, s83, 0
	global_load_dword v51, v156, s[82:83] nt
	s_add_u32 s82, s82, 0x1000
	s_addc_u32 s83, s83, 0
	global_load_dword v52, v156, s[82:83] nt
	s_add_u32 s82, s82, 0x1000
	s_addc_u32 s83, s83, 0
	global_load_dword v53, v156, s[82:83] nt
	s_add_u32 s82, s82, 0x1000
	s_addc_u32 s83, s83, 0
	global_load_dword v54, v156, s[82:83] nt
	s_add_u32 s82, s82, 0x1000
	s_addc_u32 s83, s83, 0
	global_load_dword v55, v156, s[82:83] nt
	s_add_u32 s82, s82, 0x1000
	s_addc_u32 s83, s83, 0
	global_load_dword v56, v156, s[82:83] nt
	s_add_u32 s82, s82, 0x1000
	s_addc_u32 s83, s83, 0
	global_load_dword v57, v156, s[82:83] nt
	s_add_u32 s82, s82, 0x1000
	s_addc_u32 s83, s83, 0
	global_load_dword v58, v156, s[82:83] nt
	s_add_u32 s82, s82, 0x1000
	s_addc_u32 s83, s83, 0
	global_load_dword v59, v156, s[82:83] nt
	s_add_u32 s82, s82, 0x1000
	s_addc_u32 s83, s83, 0
	global_load_dword v60, v156, s[82:83] nt
	s_add_u32 s82, s82, 0x1000
	s_addc_u32 s83, s83, 0
	global_load_dword v61, v156, s[82:83] nt
	s_add_u32 s82, s82, 0x1000
	s_addc_u32 s83, s83, 0
	global_load_dword v62, v156, s[82:83] nt
	s_add_u32 s82, s82, 0x1000
	s_addc_u32 s83, s83, 0
	global_load_dword v63, v156, s[82:83] nt
	s_add_u32 s82, s82, 0x1000
	s_addc_u32 s83, s83, 0
	global_load_dword v64, v156, s[82:83] nt
	s_add_u32 s82, s82, 0x1000
	s_addc_u32 s83, s83, 0
	global_load_dword v65, v156, s[82:83] nt
	s_add_u32 s82, s82, 0x1000
	s_addc_u32 s83, s83, 0
	global_load_dword v66, v156, s[82:83] nt
	s_add_u32 s82, s82, 0x1000
	s_addc_u32 s83, s83, 0
	global_load_dword v67, v156, s[82:83] nt
	s_add_u32 s82, s82, 0x1000
	s_addc_u32 s83, s83, 0
	global_load_dword v68, v156, s[82:83] nt
	s_add_u32 s82, s82, 0x1000
	s_addc_u32 s83, s83, 0
	global_load_dword v69, v156, s[82:83] nt
	s_add_u32 s82, s82, 0x1000
	s_addc_u32 s83, s83, 0
	global_load_dword v70, v156, s[82:83] nt
	s_add_u32 s82, s82, 0x1000
	s_addc_u32 s83, s83, 0
	global_load_dword v71, v156, s[82:83] nt
	s_add_u32 s82, s82, 0x1000
	s_addc_u32 s83, s83, 0
	global_load_dword v72, v156, s[82:83] nt
	s_add_u32 s82, s82, 0x1000
	s_addc_u32 s83, s83, 0
	global_load_dword v73, v156, s[82:83] nt
	s_add_u32 s82, s82, 0x1000
	s_addc_u32 s83, s83, 0
	global_load_dword v74, v156, s[82:83] nt
	s_add_u32 s82, s82, 0x1000
	s_addc_u32 s83, s83, 0
	global_load_dword v75, v156, s[82:83] nt
	s_add_u32 s82, s82, 0x1000
	s_addc_u32 s83, s83, 0
	global_load_dword v76, v156, s[82:83] nt
	s_add_u32 s82, s82, 0x1000
	s_addc_u32 s83, s83, 0
	global_load_dword v77, v156, s[82:83] nt
	s_add_u32 s82, s82, 0x1000
	s_addc_u32 s83, s83, 0
	global_load_dword v78, v156, s[82:83] nt
	s_add_u32 s82, s82, 0x1000
	s_addc_u32 s83, s83, 0
	global_load_dword v79, v156, s[82:83] nt
	s_add_u32 s82, s82, 0x1000
	s_addc_u32 s83, s83, 0
	global_load_dword v80, v156, s[82:83] nt
	s_add_u32 s82, s82, 0x1000
	s_addc_u32 s83, s83, 0
	global_load_dword v81, v156, s[82:83] nt
	s_add_u32 s82, s82, 0x1000
	s_addc_u32 s83, s83, 0
	global_load_dword v82, v156, s[82:83] nt
	s_add_u32 s82, s82, 0x1000
	s_addc_u32 s83, s83, 0
	global_load_dword v83, v156, s[82:83] nt
	s_add_u32 s82, s82, 0x1000
	s_addc_u32 s83, s83, 0
	global_load_dword v84, v156, s[82:83] nt
	s_add_u32 s82, s82, 0x1000
	s_addc_u32 s83, s83, 0
	global_load_dword v85, v156, s[82:83] nt
	s_add_u32 s82, s82, 0x1000
	s_addc_u32 s83, s83, 0
	global_load_dword v86, v156, s[82:83] nt
	s_add_u32 s82, s82, 0x1000
	s_addc_u32 s83, s83, 0
	global_load_dword v87, v156, s[82:83] nt
	s_add_u32 s82, s82, 0x1000
	s_addc_u32 s83, s83, 0
	global_load_dword v88, v156, s[82:83] nt
	s_add_u32 s82, s82, 0x1000
	s_addc_u32 s83, s83, 0
	global_load_dword v89, v156, s[82:83] nt
	s_add_u32 s82, s82, 0x1000
	s_addc_u32 s83, s83, 0
	global_load_dword v90, v156, s[82:83] nt
	s_add_u32 s82, s82, 0x1000
	s_addc_u32 s83, s83, 0
	global_load_dword v91, v156, s[82:83] nt
	s_add_u32 s82, s82, 0x1000
	s_addc_u32 s83, s83, 0
	global_load_dword v92, v156, s[82:83] nt
; __global__ void __launch_bounds__(NTHR, 2) hybrid_fwd(Args args) {
;     ...
;         for (int bi = blk; bi < 128; bi += G) { const int nb = bi >> 3, kl = bi & 7, k0 = kl * 64 + wave * 8, gb = (k0 >> 7) * 128, n = nb * 64 + lane;
;             float a[8];
; #pragma unroll
;             for (int kk = 0; kk < 8; ++kk) a[kk] = 0.f;
; #pragma unroll 8
;             for (int d = 0; d < 128; ++d) { const float wv = w_pool_out[(size_t)(gb + d) * 1024 + n] * pool_scale[gb + d];
; #pragma unroll
;                 for (int kk = 0; kk < 8; ++kk) a[kk] += pool_w[(size_t)(k0 + kk) * 128 + d] * wv; }
	s_add_u32 s82, s82, 0x1000
	s_addc_u32 s83, s83, 0
	global_load_dword v93, v156, s[82:83] nt
	s_add_u32 s82, s82, 0x1000
	s_addc_u32 s83, s83, 0
	global_load_dword v94, v156, s[82:83] nt
	s_add_u32 s82, s82, 0x1000
	s_addc_u32 s83, s83, 0
	global_load_dword v95, v156, s[82:83] nt
	s_add_u32 s82, s82, 0x1000
	s_addc_u32 s83, s83, 0
	global_load_dword v96, v156, s[82:83] nt
	s_add_u32 s82, s82, 0x1000
	s_addc_u32 s83, s83, 0
	global_load_dword v97, v156, s[82:83] nt
	s_add_u32 s82, s82, 0x1000
	s_addc_u32 s83, s83, 0
	global_load_dword v98, v156, s[82:83] nt
	s_add_u32 s82, s82, 0x1000
	s_addc_u32 s83, s83, 0
	global_load_dword v99, v156, s[82:83] nt
	s_add_u32 s82, s82, 0x1000
	s_addc_u32 s83, s83, 0
	global_load_dword v100, v156, s[82:83] nt
	s_add_u32 s82, s82, 0x1000
	s_addc_u32 s83, s83, 0
	global_load_dword v101, v156, s[82:83] nt
	s_add_u32 s82, s82, 0x1000
	s_addc_u32 s83, s83, 0
	global_load_dword v102, v156, s[82:83] nt
	s_add_u32 s82, s82, 0x1000
	s_addc_u32 s83, s83, 0
	global_load_dword v103, v156, s[82:83] nt
	s_add_u32 s82, s82, 0x1000
	s_addc_u32 s83, s83, 0
	global_load_dword v104, v156, s[82:83] nt
	s_add_u32 s82, s82, 0x1000
	s_addc_u32 s83, s83, 0
	global_load_dword v105, v156, s[82:83] nt
	s_add_u32 s82, s82, 0x1000
	s_addc_u32 s83, s83, 0
	global_load_dword v106, v156, s[82:83] nt
	s_add_u32 s82, s82, 0x1000
	s_addc_u32 s83, s83, 0
	global_load_dword v107, v156, s[82:83] nt
	s_add_u32 s82, s82, 0x1000
	s_addc_u32 s83, s83, 0
	global_load_dword v108, v156, s[82:83] nt
	s_add_u32 s82, s82, 0x1000
	s_addc_u32 s83, s83, 0
	global_load_dword v109, v156, s[82:83] nt
	s_add_u32 s82, s82, 0x1000
	s_addc_u32 s83, s83, 0
	global_load_dword v110, v156, s[82:83] nt
	s_add_u32 s82, s82, 0x1000
	s_addc_u32 s83, s83, 0
	global_load_dword v111, v156, s[82:83] nt
	s_add_u32 s82, s82, 0x1000
	s_addc_u32 s83, s83, 0
	global_load_dword v112, v156, s[82:83] nt
	s_add_u32 s82, s82, 0x1000
	s_addc_u32 s83, s83, 0
	global_load_dword v113, v156, s[82:83] nt
	s_add_u32 s82, s82, 0x1000
	s_addc_u32 s83, s83, 0
	global_load_dword v114, v156, s[82:83] nt
	s_add_u32 s82, s82, 0x1000
	s_addc_u32 s83, s83, 0
	global_load_dword v115, v156, s[82:83] nt
	s_add_u32 s82, s82, 0x1000
	s_addc_u32 s83, s83, 0
	global_load_dword v116, v156, s[82:83] nt
	s_add_u32 s82, s82, 0x1000
	s_addc_u32 s83, s83, 0
	global_load_dword v117, v156, s[82:83] nt
	s_add_u32 s82, s82, 0x1000
	s_addc_u32 s83, s83, 0
	global_load_dword v118, v156, s[82:83] nt
	s_add_u32 s82, s82, 0x1000
	s_addc_u32 s83, s83, 0
	global_load_dword v119, v156, s[82:83] nt
	s_add_u32 s82, s82, 0x1000
	s_addc_u32 s83, s83, 0
	global_load_dword v120, v156, s[82:83] nt
	s_add_u32 s82, s82, 0x1000
	s_addc_u32 s83, s83, 0
	global_load_dword v121, v156, s[82:83] nt
	s_add_u32 s82, s82, 0x1000
	s_addc_u32 s83, s83, 0
	global_load_dword v122, v156, s[82:83] nt
	s_add_u32 s82, s82, 0x1000
	s_addc_u32 s83, s83, 0
	global_load_dword v123, v156, s[82:83] nt
	s_add_u32 s82, s82, 0x1000
	s_addc_u32 s83, s83, 0
	global_load_dword v124, v156, s[82:83] nt
	s_add_u32 s82, s82, 0x1000
	s_addc_u32 s83, s83, 0
	global_load_dword v125, v156, s[82:83] nt
	s_add_u32 s82, s82, 0x1000
	s_addc_u32 s83, s83, 0
	global_load_dword v126, v156, s[82:83] nt
	s_add_u32 s82, s82, 0x1000
	s_addc_u32 s83, s83, 0
	global_load_dword v127, v156, s[82:83] nt
	s_lshl_b32 s79, s28, 2
	s_add_u32 s84, s10, s79
	s_addc_u32 s85, s11, 0
	global_load_dword v128, v157, s[84:85]
	global_load_dword v129, v157, s[84:85] offset:256
	s_lshl_b32 s79, s27, 9
	s_add_u32 s84, s8, s79
	s_addc_u32 s85, s9, 0
	global_load_dword v130, v157, s[84:85] offset:0
	global_load_dword v131, v157, s[84:85] offset:256
	global_load_dword v132, v157, s[84:85] offset:512
	global_load_dword v133, v157, s[84:85] offset:768
	global_load_dword v134, v157, s[84:85] offset:1024
	global_load_dword v135, v157, s[84:85] offset:1280
	global_load_dword v136, v157, s[84:85] offset:1536
	global_load_dword v137, v157, s[84:85] offset:1792
	global_load_dword v138, v157, s[84:85] offset:2048
	global_load_dword v139, v157, s[84:85] offset:2304
	global_load_dword v140, v157, s[84:85] offset:2560
	global_load_dword v141, v157, s[84:85] offset:2816
	global_load_dword v142, v157, s[84:85] offset:3072
	global_load_dword v143, v157, s[84:85] offset:3328
	global_load_dword v144, v157, s[84:85] offset:3584
	global_load_dword v145, v157, s[84:85] offset:3840
	v_mov_b32_e32 v146, 0
	v_mov_b32_e32 v147, 0
	v_mov_b32_e32 v148, 0
	v_mov_b32_e32 v149, 0
	v_mov_b32_e32 v150, 0
	v_mov_b32_e32 v151, 0
	v_mov_b32_e32 v152, 0
	v_mov_b32_e32 v153, 0
	s_waitcnt vmcnt(0)
; __global__ void __launch_bounds__(NTHR, 2) hybrid_fwd(Args args) {
;     ...
; #pragma unroll 8
;             for (int d = 0; d < 128; ++d) { const float wv = w_pool_out[(size_t)(gb + d) * 1024 + n] * pool_scale[gb + d];
; #pragma unroll
;                 for (int kk = 0; kk < 8; ++kk) a[kk] += pool_w[(size_t)(k0 + kk) * 128 + d] * wv; }
	s_nop 0
	v_readlane_b32 s88, v128, 0
	v_readlane_b32 s77, v130, 0
	v_readlane_b32 s78, v132, 0
	v_readlane_b32 s79, v134, 0
	v_readlane_b32 s80, v136, 0
	v_readlane_b32 s81, v138, 0
	v_readlane_b32 s82, v140, 0
	v_readlane_b32 s83, v142, 0
	v_readlane_b32 s84, v144, 0
	v_mul_f32_e32 v154, s88, v0
	v_fmac_f32_e32 v146, s77, v154
	v_fmac_f32_e32 v147, s78, v154
	v_fmac_f32_e32 v148, s79, v154
	v_fmac_f32_e32 v149, s80, v154
	v_fmac_f32_e32 v150, s81, v154
	v_fmac_f32_e32 v151, s82, v154
	v_fmac_f32_e32 v152, s83, v154
	v_fmac_f32_e32 v153, s84, v154
	v_readlane_b32 s88, v128, 1
	v_readlane_b32 s77, v130, 1
	v_readlane_b32 s78, v132, 1
	v_readlane_b32 s79, v134, 1
	v_readlane_b32 s80, v136, 1
	v_readlane_b32 s81, v138, 1
	v_readlane_b32 s82, v140, 1
	v_readlane_b32 s83, v142, 1
	v_readlane_b32 s84, v144, 1
	v_mul_f32_e32 v154, s88, v1
	v_fmac_f32_e32 v146, s77, v154
	v_fmac_f32_e32 v147, s78, v154
	v_fmac_f32_e32 v148, s79, v154
	v_fmac_f32_e32 v149, s80, v154
	v_fmac_f32_e32 v150, s81, v154
	v_fmac_f32_e32 v151, s82, v154
	v_fmac_f32_e32 v152, s83, v154
	v_fmac_f32_e32 v153, s84, v154
	v_readlane_b32 s88, v128, 2
	v_readlane_b32 s77, v130, 2
	v_readlane_b32 s78, v132, 2
	v_readlane_b32 s79, v134, 2
	v_readlane_b32 s80, v136, 2
	v_readlane_b32 s81, v138, 2
	v_readlane_b32 s82, v140, 2
	v_readlane_b32 s83, v142, 2
	v_readlane_b32 s84, v144, 2
	v_mul_f32_e32 v154, s88, v2
	v_fmac_f32_e32 v146, s77, v154
	v_fmac_f32_e32 v147, s78, v154
	v_fmac_f32_e32 v148, s79, v154
	v_fmac_f32_e32 v149, s80, v154
	v_fmac_f32_e32 v150, s81, v154
	v_fmac_f32_e32 v151, s82, v154
	v_fmac_f32_e32 v152, s83, v154
	v_fmac_f32_e32 v153, s84, v154
	v_readlane_b32 s88, v128, 3
	v_readlane_b32 s77, v130, 3
	v_readlane_b32 s78, v132, 3
	v_readlane_b32 s79, v134, 3
	v_readlane_b32 s80, v136, 3
	v_readlane_b32 s81, v138, 3
	v_readlane_b32 s82, v140, 3
	v_readlane_b32 s83, v142, 3
	v_readlane_b32 s84, v144, 3
	v_mul_f32_e32 v154, s88, v3
	v_fmac_f32_e32 v146, s77, v154
	v_fmac_f32_e32 v147, s78, v154
	v_fmac_f32_e32 v148, s79, v154
	v_fmac_f32_e32 v149, s80, v154
	v_fmac_f32_e32 v150, s81, v154
	v_fmac_f32_e32 v151, s82, v154
	v_fmac_f32_e32 v152, s83, v154
	v_fmac_f32_e32 v153, s84, v154
	v_readlane_b32 s88, v128, 4
	v_readlane_b32 s77, v130, 4
	v_readlane_b32 s78, v132, 4
	v_readlane_b32 s79, v134, 4
	v_readlane_b32 s80, v136, 4
	v_readlane_b32 s81, v138, 4
	v_readlane_b32 s82, v140, 4
	v_readlane_b32 s83, v142, 4
	v_readlane_b32 s84, v144, 4
	v_mul_f32_e32 v154, s88, v4
	v_fmac_f32_e32 v146, s77, v154
	v_fmac_f32_e32 v147, s78, v154
	v_fmac_f32_e32 v148, s79, v154
	v_fmac_f32_e32 v149, s80, v154
	v_fmac_f32_e32 v150, s81, v154
	v_fmac_f32_e32 v151, s82, v154
	v_fmac_f32_e32 v152, s83, v154
	v_fmac_f32_e32 v153, s84, v154
	v_readlane_b32 s88, v128, 5
	v_readlane_b32 s77, v130, 5
	v_readlane_b32 s78, v132, 5
	v_readlane_b32 s79, v134, 5
	v_readlane_b32 s80, v136, 5
	v_readlane_b32 s81, v138, 5
	v_readlane_b32 s82, v140, 5
	v_readlane_b32 s83, v142, 5
	v_readlane_b32 s84, v144, 5
	v_mul_f32_e32 v154, s88, v5
	v_fmac_f32_e32 v146, s77, v154
	v_fmac_f32_e32 v147, s78, v154
	v_fmac_f32_e32 v148, s79, v154
	v_fmac_f32_e32 v149, s80, v154
	v_fmac_f32_e32 v150, s81, v154
	v_fmac_f32_e32 v151, s82, v154
	v_fmac_f32_e32 v152, s83, v154
	v_fmac_f32_e32 v153, s84, v154
	v_readlane_b32 s88, v128, 6
	v_readlane_b32 s77, v130, 6
	v_readlane_b32 s78, v132, 6
	v_readlane_b32 s79, v134, 6
	v_readlane_b32 s80, v136, 6
	v_readlane_b32 s81, v138, 6
	v_readlane_b32 s82, v140, 6
	v_readlane_b32 s83, v142, 6
	v_readlane_b32 s84, v144, 6
	v_mul_f32_e32 v154, s88, v6
	v_fmac_f32_e32 v146, s77, v154
	v_fmac_f32_e32 v147, s78, v154
	v_fmac_f32_e32 v148, s79, v154
	v_fmac_f32_e32 v149, s80, v154
	v_fmac_f32_e32 v150, s81, v154
	v_fmac_f32_e32 v151, s82, v154
	v_fmac_f32_e32 v152, s83, v154
	v_fmac_f32_e32 v153, s84, v154
	v_readlane_b32 s88, v128, 7
	v_readlane_b32 s77, v130, 7
	v_readlane_b32 s78, v132, 7
	v_readlane_b32 s79, v134, 7
	v_readlane_b32 s80, v136, 7
	v_readlane_b32 s81, v138, 7
	v_readlane_b32 s82, v140, 7
	v_readlane_b32 s83, v142, 7
	v_readlane_b32 s84, v144, 7
	v_mul_f32_e32 v154, s88, v7
	v_fmac_f32_e32 v146, s77, v154
	v_fmac_f32_e32 v147, s78, v154
	v_fmac_f32_e32 v148, s79, v154
	v_fmac_f32_e32 v149, s80, v154
	v_fmac_f32_e32 v150, s81, v154
	v_fmac_f32_e32 v151, s82, v154
	v_fmac_f32_e32 v152, s83, v154
	v_fmac_f32_e32 v153, s84, v154
	v_readlane_b32 s88, v128, 8
	v_readlane_b32 s77, v130, 8
	v_readlane_b32 s78, v132, 8
	v_readlane_b32 s79, v134, 8
	v_readlane_b32 s80, v136, 8
	v_readlane_b32 s81, v138, 8
	v_readlane_b32 s82, v140, 8
	v_readlane_b32 s83, v142, 8
	v_readlane_b32 s84, v144, 8
	v_mul_f32_e32 v154, s88, v8
	v_fmac_f32_e32 v146, s77, v154
	v_fmac_f32_e32 v147, s78, v154
	v_fmac_f32_e32 v148, s79, v154
	v_fmac_f32_e32 v149, s80, v154
	v_fmac_f32_e32 v150, s81, v154
	v_fmac_f32_e32 v151, s82, v154
	v_fmac_f32_e32 v152, s83, v154
	v_fmac_f32_e32 v153, s84, v154
	v_readlane_b32 s88, v128, 9
	v_readlane_b32 s77, v130, 9
	v_readlane_b32 s78, v132, 9
	v_readlane_b32 s79, v134, 9
	v_readlane_b32 s80, v136, 9
	v_readlane_b32 s81, v138, 9
	v_readlane_b32 s82, v140, 9
	v_readlane_b32 s83, v142, 9
	v_readlane_b32 s84, v144, 9
	v_mul_f32_e32 v154, s88, v9
	v_fmac_f32_e32 v146, s77, v154
	v_fmac_f32_e32 v147, s78, v154
	v_fmac_f32_e32 v148, s79, v154
	v_fmac_f32_e32 v149, s80, v154
	v_fmac_f32_e32 v150, s81, v154
	v_fmac_f32_e32 v151, s82, v154
	v_fmac_f32_e32 v152, s83, v154
	v_fmac_f32_e32 v153, s84, v154
	v_readlane_b32 s88, v128, 10
	v_readlane_b32 s77, v130, 10
	v_readlane_b32 s78, v132, 10
	v_readlane_b32 s79, v134, 10
	v_readlane_b32 s80, v136, 10
	v_readlane_b32 s81, v138, 10
; __global__ void __launch_bounds__(NTHR, 2) hybrid_fwd(Args args) {
;     ...
; #pragma unroll 8
;             for (int d = 0; d < 128; ++d) { const float wv = w_pool_out[(size_t)(gb + d) * 1024 + n] * pool_scale[gb + d];
; #pragma unroll
;                 for (int kk = 0; kk < 8; ++kk) a[kk] += pool_w[(size_t)(k0 + kk) * 128 + d] * wv; }
	v_readlane_b32 s82, v140, 10
	v_readlane_b32 s83, v142, 10
	v_readlane_b32 s84, v144, 10
	v_mul_f32_e32 v154, s88, v10
	v_fmac_f32_e32 v146, s77, v154
	v_fmac_f32_e32 v147, s78, v154
	v_fmac_f32_e32 v148, s79, v154
	v_fmac_f32_e32 v149, s80, v154
	v_fmac_f32_e32 v150, s81, v154
	v_fmac_f32_e32 v151, s82, v154
	v_fmac_f32_e32 v152, s83, v154
	v_fmac_f32_e32 v153, s84, v154
	v_readlane_b32 s88, v128, 11
	v_readlane_b32 s77, v130, 11
	v_readlane_b32 s78, v132, 11
	v_readlane_b32 s79, v134, 11
	v_readlane_b32 s80, v136, 11
	v_readlane_b32 s81, v138, 11
	v_readlane_b32 s82, v140, 11
	v_readlane_b32 s83, v142, 11
	v_readlane_b32 s84, v144, 11
	v_mul_f32_e32 v154, s88, v11
	v_fmac_f32_e32 v146, s77, v154
	v_fmac_f32_e32 v147, s78, v154
	v_fmac_f32_e32 v148, s79, v154
	v_fmac_f32_e32 v149, s80, v154
	v_fmac_f32_e32 v150, s81, v154
	v_fmac_f32_e32 v151, s82, v154
	v_fmac_f32_e32 v152, s83, v154
	v_fmac_f32_e32 v153, s84, v154
	v_readlane_b32 s88, v128, 12
	v_readlane_b32 s77, v130, 12
	v_readlane_b32 s78, v132, 12
	v_readlane_b32 s79, v134, 12
	v_readlane_b32 s80, v136, 12
	v_readlane_b32 s81, v138, 12
	v_readlane_b32 s82, v140, 12
	v_readlane_b32 s83, v142, 12
	v_readlane_b32 s84, v144, 12
	v_mul_f32_e32 v154, s88, v12
	v_fmac_f32_e32 v146, s77, v154
	v_fmac_f32_e32 v147, s78, v154
	v_fmac_f32_e32 v148, s79, v154
	v_fmac_f32_e32 v149, s80, v154
	v_fmac_f32_e32 v150, s81, v154
	v_fmac_f32_e32 v151, s82, v154
	v_fmac_f32_e32 v152, s83, v154
	v_fmac_f32_e32 v153, s84, v154
	v_readlane_b32 s88, v128, 13
	v_readlane_b32 s77, v130, 13
	v_readlane_b32 s78, v132, 13
	v_readlane_b32 s79, v134, 13
	v_readlane_b32 s80, v136, 13
	v_readlane_b32 s81, v138, 13
	v_readlane_b32 s82, v140, 13
	v_readlane_b32 s83, v142, 13
	v_readlane_b32 s84, v144, 13
	v_mul_f32_e32 v154, s88, v13
	v_fmac_f32_e32 v146, s77, v154
	v_fmac_f32_e32 v147, s78, v154
	v_fmac_f32_e32 v148, s79, v154
	v_fmac_f32_e32 v149, s80, v154
	v_fmac_f32_e32 v150, s81, v154
	v_fmac_f32_e32 v151, s82, v154
	v_fmac_f32_e32 v152, s83, v154
	v_fmac_f32_e32 v153, s84, v154
	v_readlane_b32 s88, v128, 14
	v_readlane_b32 s77, v130, 14
	v_readlane_b32 s78, v132, 14
	v_readlane_b32 s79, v134, 14
	v_readlane_b32 s80, v136, 14
	v_readlane_b32 s81, v138, 14
	v_readlane_b32 s82, v140, 14
	v_readlane_b32 s83, v142, 14
	v_readlane_b32 s84, v144, 14
	v_mul_f32_e32 v154, s88, v14
	v_fmac_f32_e32 v146, s77, v154
	v_fmac_f32_e32 v147, s78, v154
	v_fmac_f32_e32 v148, s79, v154
	v_fmac_f32_e32 v149, s80, v154
	v_fmac_f32_e32 v150, s81, v154
	v_fmac_f32_e32 v151, s82, v154
	v_fmac_f32_e32 v152, s83, v154
	v_fmac_f32_e32 v153, s84, v154
	v_readlane_b32 s88, v128, 15
	v_readlane_b32 s77, v130, 15
	v_readlane_b32 s78, v132, 15
	v_readlane_b32 s79, v134, 15
	v_readlane_b32 s80, v136, 15
	v_readlane_b32 s81, v138, 15
	v_readlane_b32 s82, v140, 15
	v_readlane_b32 s83, v142, 15
	v_readlane_b32 s84, v144, 15
	v_mul_f32_e32 v154, s88, v15
	v_fmac_f32_e32 v146, s77, v154
	v_fmac_f32_e32 v147, s78, v154
	v_fmac_f32_e32 v148, s79, v154
	v_fmac_f32_e32 v149, s80, v154
	v_fmac_f32_e32 v150, s81, v154
	v_fmac_f32_e32 v151, s82, v154
	v_fmac_f32_e32 v152, s83, v154
	v_fmac_f32_e32 v153, s84, v154
	v_readlane_b32 s88, v128, 16
	v_readlane_b32 s77, v130, 16
	v_readlane_b32 s78, v132, 16
	v_readlane_b32 s79, v134, 16
	v_readlane_b32 s80, v136, 16
	v_readlane_b32 s81, v138, 16
	v_readlane_b32 s82, v140, 16
	v_readlane_b32 s83, v142, 16
	v_readlane_b32 s84, v144, 16
	v_mul_f32_e32 v154, s88, v16
	v_fmac_f32_e32 v146, s77, v154
	v_fmac_f32_e32 v147, s78, v154
	v_fmac_f32_e32 v148, s79, v154
	v_fmac_f32_e32 v149, s80, v154
	v_fmac_f32_e32 v150, s81, v154
	v_fmac_f32_e32 v151, s82, v154
	v_fmac_f32_e32 v152, s83, v154
	v_fmac_f32_e32 v153, s84, v154
	v_readlane_b32 s88, v128, 17
	v_readlane_b32 s77, v130, 17
	v_readlane_b32 s78, v132, 17
	v_readlane_b32 s79, v134, 17
	v_readlane_b32 s80, v136, 17
	v_readlane_b32 s81, v138, 17
	v_readlane_b32 s82, v140, 17
	v_readlane_b32 s83, v142, 17
	v_readlane_b32 s84, v144, 17
	v_mul_f32_e32 v154, s88, v17
	v_fmac_f32_e32 v146, s77, v154
	v_fmac_f32_e32 v147, s78, v154
	v_fmac_f32_e32 v148, s79, v154
	v_fmac_f32_e32 v149, s80, v154
	v_fmac_f32_e32 v150, s81, v154
	v_fmac_f32_e32 v151, s82, v154
	v_fmac_f32_e32 v152, s83, v154
	v_fmac_f32_e32 v153, s84, v154
	v_readlane_b32 s88, v128, 18
	v_readlane_b32 s77, v130, 18
	v_readlane_b32 s78, v132, 18
	v_readlane_b32 s79, v134, 18
	v_readlane_b32 s80, v136, 18
	v_readlane_b32 s81, v138, 18
	v_readlane_b32 s82, v140, 18
	v_readlane_b32 s83, v142, 18
	v_readlane_b32 s84, v144, 18
	v_mul_f32_e32 v154, s88, v18
	v_fmac_f32_e32 v146, s77, v154
	v_fmac_f32_e32 v147, s78, v154
	v_fmac_f32_e32 v148, s79, v154
	v_fmac_f32_e32 v149, s80, v154
	v_fmac_f32_e32 v150, s81, v154
	v_fmac_f32_e32 v151, s82, v154
	v_fmac_f32_e32 v152, s83, v154
	v_fmac_f32_e32 v153, s84, v154
	v_readlane_b32 s88, v128, 19
	v_readlane_b32 s77, v130, 19
	v_readlane_b32 s78, v132, 19
	v_readlane_b32 s79, v134, 19
	v_readlane_b32 s80, v136, 19
	v_readlane_b32 s81, v138, 19
	v_readlane_b32 s82, v140, 19
	v_readlane_b32 s83, v142, 19
	v_readlane_b32 s84, v144, 19
	v_mul_f32_e32 v154, s88, v19
	v_fmac_f32_e32 v146, s77, v154
	v_fmac_f32_e32 v147, s78, v154
	v_fmac_f32_e32 v148, s79, v154
	v_fmac_f32_e32 v149, s80, v154
	v_fmac_f32_e32 v150, s81, v154
	v_fmac_f32_e32 v151, s82, v154
	v_fmac_f32_e32 v152, s83, v154
	v_fmac_f32_e32 v153, s84, v154
	v_readlane_b32 s88, v128, 20
	v_readlane_b32 s77, v130, 20
	v_readlane_b32 s78, v132, 20
	v_readlane_b32 s79, v134, 20
	v_readlane_b32 s80, v136, 20
	v_readlane_b32 s81, v138, 20
	v_readlane_b32 s82, v140, 20
	v_readlane_b32 s83, v142, 20
	v_readlane_b32 s84, v144, 20
; __global__ void __launch_bounds__(NTHR, 2) hybrid_fwd(Args args) {
;     ...
; #pragma unroll 8
;             for (int d = 0; d < 128; ++d) { const float wv = w_pool_out[(size_t)(gb + d) * 1024 + n] * pool_scale[gb + d];
; #pragma unroll
;                 for (int kk = 0; kk < 8; ++kk) a[kk] += pool_w[(size_t)(k0 + kk) * 128 + d] * wv; }
	v_mul_f32_e32 v154, s88, v20
	v_fmac_f32_e32 v146, s77, v154
	v_fmac_f32_e32 v147, s78, v154
	v_fmac_f32_e32 v148, s79, v154
	v_fmac_f32_e32 v149, s80, v154
	v_fmac_f32_e32 v150, s81, v154
	v_fmac_f32_e32 v151, s82, v154
	v_fmac_f32_e32 v152, s83, v154
	v_fmac_f32_e32 v153, s84, v154
	v_readlane_b32 s88, v128, 21
	v_readlane_b32 s77, v130, 21
	v_readlane_b32 s78, v132, 21
	v_readlane_b32 s79, v134, 21
	v_readlane_b32 s80, v136, 21
	v_readlane_b32 s81, v138, 21
	v_readlane_b32 s82, v140, 21
	v_readlane_b32 s83, v142, 21
	v_readlane_b32 s84, v144, 21
	v_mul_f32_e32 v154, s88, v21
	v_fmac_f32_e32 v146, s77, v154
	v_fmac_f32_e32 v147, s78, v154
	v_fmac_f32_e32 v148, s79, v154
	v_fmac_f32_e32 v149, s80, v154
	v_fmac_f32_e32 v150, s81, v154
	v_fmac_f32_e32 v151, s82, v154
	v_fmac_f32_e32 v152, s83, v154
	v_fmac_f32_e32 v153, s84, v154
	v_readlane_b32 s88, v128, 22
	v_readlane_b32 s77, v130, 22
	v_readlane_b32 s78, v132, 22
	v_readlane_b32 s79, v134, 22
	v_readlane_b32 s80, v136, 22
	v_readlane_b32 s81, v138, 22
	v_readlane_b32 s82, v140, 22
	v_readlane_b32 s83, v142, 22
	v_readlane_b32 s84, v144, 22
	v_mul_f32_e32 v154, s88, v22
	v_fmac_f32_e32 v146, s77, v154
	v_fmac_f32_e32 v147, s78, v154
	v_fmac_f32_e32 v148, s79, v154
	v_fmac_f32_e32 v149, s80, v154
	v_fmac_f32_e32 v150, s81, v154
	v_fmac_f32_e32 v151, s82, v154
	v_fmac_f32_e32 v152, s83, v154
	v_fmac_f32_e32 v153, s84, v154
	v_readlane_b32 s88, v128, 23
	v_readlane_b32 s77, v130, 23
	v_readlane_b32 s78, v132, 23
	v_readlane_b32 s79, v134, 23
	v_readlane_b32 s80, v136, 23
	v_readlane_b32 s81, v138, 23
	v_readlane_b32 s82, v140, 23
	v_readlane_b32 s83, v142, 23
	v_readlane_b32 s84, v144, 23
	v_mul_f32_e32 v154, s88, v23
	v_fmac_f32_e32 v146, s77, v154
	v_fmac_f32_e32 v147, s78, v154
	v_fmac_f32_e32 v148, s79, v154
	v_fmac_f32_e32 v149, s80, v154
	v_fmac_f32_e32 v150, s81, v154
	v_fmac_f32_e32 v151, s82, v154
	v_fmac_f32_e32 v152, s83, v154
	v_fmac_f32_e32 v153, s84, v154
	v_readlane_b32 s88, v128, 24
	v_readlane_b32 s77, v130, 24
	v_readlane_b32 s78, v132, 24
	v_readlane_b32 s79, v134, 24
	v_readlane_b32 s80, v136, 24
	v_readlane_b32 s81, v138, 24
	v_readlane_b32 s82, v140, 24
	v_readlane_b32 s83, v142, 24
	v_readlane_b32 s84, v144, 24
	v_mul_f32_e32 v154, s88, v24
	v_fmac_f32_e32 v146, s77, v154
	v_fmac_f32_e32 v147, s78, v154
	v_fmac_f32_e32 v148, s79, v154
	v_fmac_f32_e32 v149, s80, v154
	v_fmac_f32_e32 v150, s81, v154
	v_fmac_f32_e32 v151, s82, v154
	v_fmac_f32_e32 v152, s83, v154
	v_fmac_f32_e32 v153, s84, v154
	v_readlane_b32 s88, v128, 25
	v_readlane_b32 s77, v130, 25
	v_readlane_b32 s78, v132, 25
	v_readlane_b32 s79, v134, 25
	v_readlane_b32 s80, v136, 25
	v_readlane_b32 s81, v138, 25
	v_readlane_b32 s82, v140, 25
	v_readlane_b32 s83, v142, 25
	v_readlane_b32 s84, v144, 25
	v_mul_f32_e32 v154, s88, v25
	v_fmac_f32_e32 v146, s77, v154
	v_fmac_f32_e32 v147, s78, v154
	v_fmac_f32_e32 v148, s79, v154
	v_fmac_f32_e32 v149, s80, v154
	v_fmac_f32_e32 v150, s81, v154
	v_fmac_f32_e32 v151, s82, v154
	v_fmac_f32_e32 v152, s83, v154
	v_fmac_f32_e32 v153, s84, v154
	v_readlane_b32 s88, v128, 26
	v_readlane_b32 s77, v130, 26
	v_readlane_b32 s78, v132, 26
	v_readlane_b32 s79, v134, 26
	v_readlane_b32 s80, v136, 26
	v_readlane_b32 s81, v138, 26
	v_readlane_b32 s82, v140, 26
	v_readlane_b32 s83, v142, 26
	v_readlane_b32 s84, v144, 26
	v_mul_f32_e32 v154, s88, v26
	v_fmac_f32_e32 v146, s77, v154
	v_fmac_f32_e32 v147, s78, v154
	v_fmac_f32_e32 v148, s79, v154
	v_fmac_f32_e32 v149, s80, v154
	v_fmac_f32_e32 v150, s81, v154
	v_fmac_f32_e32 v151, s82, v154
	v_fmac_f32_e32 v152, s83, v154
	v_fmac_f32_e32 v153, s84, v154
	v_readlane_b32 s88, v128, 27
	v_readlane_b32 s77, v130, 27
	v_readlane_b32 s78, v132, 27
	v_readlane_b32 s79, v134, 27
	v_readlane_b32 s80, v136, 27
	v_readlane_b32 s81, v138, 27
	v_readlane_b32 s82, v140, 27
	v_readlane_b32 s83, v142, 27
	v_readlane_b32 s84, v144, 27
	v_mul_f32_e32 v154, s88, v27
	v_fmac_f32_e32 v146, s77, v154
	v_fmac_f32_e32 v147, s78, v154
	v_fmac_f32_e32 v148, s79, v154
	v_fmac_f32_e32 v149, s80, v154
	v_fmac_f32_e32 v150, s81, v154
	v_fmac_f32_e32 v151, s82, v154
	v_fmac_f32_e32 v152, s83, v154
	v_fmac_f32_e32 v153, s84, v154
	v_readlane_b32 s88, v128, 28
	v_readlane_b32 s77, v130, 28
	v_readlane_b32 s78, v132, 28
	v_readlane_b32 s79, v134, 28
	v_readlane_b32 s80, v136, 28
	v_readlane_b32 s81, v138, 28
	v_readlane_b32 s82, v140, 28
	v_readlane_b32 s83, v142, 28
	v_readlane_b32 s84, v144, 28
	v_mul_f32_e32 v154, s88, v28
	v_fmac_f32_e32 v146, s77, v154
	v_fmac_f32_e32 v147, s78, v154
	v_fmac_f32_e32 v148, s79, v154
	v_fmac_f32_e32 v149, s80, v154
	v_fmac_f32_e32 v150, s81, v154
	v_fmac_f32_e32 v151, s82, v154
	v_fmac_f32_e32 v152, s83, v154
	v_fmac_f32_e32 v153, s84, v154
	v_readlane_b32 s88, v128, 29
	v_readlane_b32 s77, v130, 29
	v_readlane_b32 s78, v132, 29
	v_readlane_b32 s79, v134, 29
	v_readlane_b32 s80, v136, 29
	v_readlane_b32 s81, v138, 29
	v_readlane_b32 s82, v140, 29
	v_readlane_b32 s83, v142, 29
	v_readlane_b32 s84, v144, 29
	v_mul_f32_e32 v154, s88, v29
	v_fmac_f32_e32 v146, s77, v154
	v_fmac_f32_e32 v147, s78, v154
	v_fmac_f32_e32 v148, s79, v154
	v_fmac_f32_e32 v149, s80, v154
	v_fmac_f32_e32 v150, s81, v154
	v_fmac_f32_e32 v151, s82, v154
	v_fmac_f32_e32 v152, s83, v154
	v_fmac_f32_e32 v153, s84, v154
	v_readlane_b32 s88, v128, 30
	v_readlane_b32 s77, v130, 30
	v_readlane_b32 s78, v132, 30
	v_readlane_b32 s79, v134, 30
	v_readlane_b32 s80, v136, 30
	v_readlane_b32 s81, v138, 30
	v_readlane_b32 s82, v140, 30
	v_readlane_b32 s83, v142, 30
	v_readlane_b32 s84, v144, 30
	v_mul_f32_e32 v154, s88, v30
	v_fmac_f32_e32 v146, s77, v154
	v_fmac_f32_e32 v147, s78, v154
; __global__ void __launch_bounds__(NTHR, 2) hybrid_fwd(Args args) {
;     ...
; #pragma unroll 8
;             for (int d = 0; d < 128; ++d) { const float wv = w_pool_out[(size_t)(gb + d) * 1024 + n] * pool_scale[gb + d];
; #pragma unroll
;                 for (int kk = 0; kk < 8; ++kk) a[kk] += pool_w[(size_t)(k0 + kk) * 128 + d] * wv; }
	v_fmac_f32_e32 v148, s79, v154
	v_fmac_f32_e32 v149, s80, v154
	v_fmac_f32_e32 v150, s81, v154
	v_fmac_f32_e32 v151, s82, v154
	v_fmac_f32_e32 v152, s83, v154
	v_fmac_f32_e32 v153, s84, v154
	v_readlane_b32 s88, v128, 31
	v_readlane_b32 s77, v130, 31
	v_readlane_b32 s78, v132, 31
	v_readlane_b32 s79, v134, 31
	v_readlane_b32 s80, v136, 31
	v_readlane_b32 s81, v138, 31
	v_readlane_b32 s82, v140, 31
	v_readlane_b32 s83, v142, 31
	v_readlane_b32 s84, v144, 31
	v_mul_f32_e32 v154, s88, v31
	v_fmac_f32_e32 v146, s77, v154
	v_fmac_f32_e32 v147, s78, v154
	v_fmac_f32_e32 v148, s79, v154
	v_fmac_f32_e32 v149, s80, v154
	v_fmac_f32_e32 v150, s81, v154
	v_fmac_f32_e32 v151, s82, v154
	v_fmac_f32_e32 v152, s83, v154
	v_fmac_f32_e32 v153, s84, v154
	v_readlane_b32 s88, v128, 32
	v_readlane_b32 s77, v130, 32
	v_readlane_b32 s78, v132, 32
	v_readlane_b32 s79, v134, 32
	v_readlane_b32 s80, v136, 32
	v_readlane_b32 s81, v138, 32
	v_readlane_b32 s82, v140, 32
	v_readlane_b32 s83, v142, 32
	v_readlane_b32 s84, v144, 32
	v_mul_f32_e32 v154, s88, v32
	v_fmac_f32_e32 v146, s77, v154
	v_fmac_f32_e32 v147, s78, v154
	v_fmac_f32_e32 v148, s79, v154
	v_fmac_f32_e32 v149, s80, v154
	v_fmac_f32_e32 v150, s81, v154
	v_fmac_f32_e32 v151, s82, v154
	v_fmac_f32_e32 v152, s83, v154
	v_fmac_f32_e32 v153, s84, v154
	v_readlane_b32 s88, v128, 33
	v_readlane_b32 s77, v130, 33
	v_readlane_b32 s78, v132, 33
	v_readlane_b32 s79, v134, 33
	v_readlane_b32 s80, v136, 33
	v_readlane_b32 s81, v138, 33
	v_readlane_b32 s82, v140, 33
	v_readlane_b32 s83, v142, 33
	v_readlane_b32 s84, v144, 33
	v_mul_f32_e32 v154, s88, v33
	v_fmac_f32_e32 v146, s77, v154
	v_fmac_f32_e32 v147, s78, v154
	v_fmac_f32_e32 v148, s79, v154
	v_fmac_f32_e32 v149, s80, v154
	v_fmac_f32_e32 v150, s81, v154
	v_fmac_f32_e32 v151, s82, v154
	v_fmac_f32_e32 v152, s83, v154
	v_fmac_f32_e32 v153, s84, v154
	v_readlane_b32 s88, v128, 34
	v_readlane_b32 s77, v130, 34
	v_readlane_b32 s78, v132, 34
	v_readlane_b32 s79, v134, 34
	v_readlane_b32 s80, v136, 34
	v_readlane_b32 s81, v138, 34
	v_readlane_b32 s82, v140, 34
	v_readlane_b32 s83, v142, 34
	v_readlane_b32 s84, v144, 34
	v_mul_f32_e32 v154, s88, v34
	v_fmac_f32_e32 v146, s77, v154
	v_fmac_f32_e32 v147, s78, v154
	v_fmac_f32_e32 v148, s79, v154
	v_fmac_f32_e32 v149, s80, v154
	v_fmac_f32_e32 v150, s81, v154
	v_fmac_f32_e32 v151, s82, v154
	v_fmac_f32_e32 v152, s83, v154
	v_fmac_f32_e32 v153, s84, v154
	v_readlane_b32 s88, v128, 35
	v_readlane_b32 s77, v130, 35
	v_readlane_b32 s78, v132, 35
	v_readlane_b32 s79, v134, 35
	v_readlane_b32 s80, v136, 35
	v_readlane_b32 s81, v138, 35
	v_readlane_b32 s82, v140, 35
	v_readlane_b32 s83, v142, 35
	v_readlane_b32 s84, v144, 35
	v_mul_f32_e32 v154, s88, v35
	v_fmac_f32_e32 v146, s77, v154
	v_fmac_f32_e32 v147, s78, v154
	v_fmac_f32_e32 v148, s79, v154
	v_fmac_f32_e32 v149, s80, v154
	v_fmac_f32_e32 v150, s81, v154
	v_fmac_f32_e32 v151, s82, v154
	v_fmac_f32_e32 v152, s83, v154
	v_fmac_f32_e32 v153, s84, v154
	v_readlane_b32 s88, v128, 36
	v_readlane_b32 s77, v130, 36
	v_readlane_b32 s78, v132, 36
	v_readlane_b32 s79, v134, 36
	v_readlane_b32 s80, v136, 36
	v_readlane_b32 s81, v138, 36
	v_readlane_b32 s82, v140, 36
	v_readlane_b32 s83, v142, 36
	v_readlane_b32 s84, v144, 36
	v_mul_f32_e32 v154, s88, v36
	v_fmac_f32_e32 v146, s77, v154
	v_fmac_f32_e32 v147, s78, v154
	v_fmac_f32_e32 v148, s79, v154
	v_fmac_f32_e32 v149, s80, v154
	v_fmac_f32_e32 v150, s81, v154
	v_fmac_f32_e32 v151, s82, v154
	v_fmac_f32_e32 v152, s83, v154
	v_fmac_f32_e32 v153, s84, v154
	v_readlane_b32 s88, v128, 37
	v_readlane_b32 s77, v130, 37
	v_readlane_b32 s78, v132, 37
	v_readlane_b32 s79, v134, 37
	v_readlane_b32 s80, v136, 37
	v_readlane_b32 s81, v138, 37
	v_readlane_b32 s82, v140, 37
	v_readlane_b32 s83, v142, 37
	v_readlane_b32 s84, v144, 37
	v_mul_f32_e32 v154, s88, v37
	v_fmac_f32_e32 v146, s77, v154
	v_fmac_f32_e32 v147, s78, v154
	v_fmac_f32_e32 v148, s79, v154
	v_fmac_f32_e32 v149, s80, v154
	v_fmac_f32_e32 v150, s81, v154
	v_fmac_f32_e32 v151, s82, v154
	v_fmac_f32_e32 v152, s83, v154
	v_fmac_f32_e32 v153, s84, v154
	v_readlane_b32 s88, v128, 38
	v_readlane_b32 s77, v130, 38
	v_readlane_b32 s78, v132, 38
	v_readlane_b32 s79, v134, 38
	v_readlane_b32 s80, v136, 38
	v_readlane_b32 s81, v138, 38
	v_readlane_b32 s82, v140, 38
	v_readlane_b32 s83, v142, 38
	v_readlane_b32 s84, v144, 38
	v_mul_f32_e32 v154, s88, v38
	v_fmac_f32_e32 v146, s77, v154
	v_fmac_f32_e32 v147, s78, v154
	v_fmac_f32_e32 v148, s79, v154
	v_fmac_f32_e32 v149, s80, v154
	v_fmac_f32_e32 v150, s81, v154
	v_fmac_f32_e32 v151, s82, v154
	v_fmac_f32_e32 v152, s83, v154
	v_fmac_f32_e32 v153, s84, v154
	v_readlane_b32 s88, v128, 39
	v_readlane_b32 s77, v130, 39
	v_readlane_b32 s78, v132, 39
	v_readlane_b32 s79, v134, 39
	v_readlane_b32 s80, v136, 39
	v_readlane_b32 s81, v138, 39
	v_readlane_b32 s82, v140, 39
	v_readlane_b32 s83, v142, 39
	v_readlane_b32 s84, v144, 39
	v_mul_f32_e32 v154, s88, v39
	v_fmac_f32_e32 v146, s77, v154
	v_fmac_f32_e32 v147, s78, v154
	v_fmac_f32_e32 v148, s79, v154
	v_fmac_f32_e32 v149, s80, v154
	v_fmac_f32_e32 v150, s81, v154
	v_fmac_f32_e32 v151, s82, v154
	v_fmac_f32_e32 v152, s83, v154
	v_fmac_f32_e32 v153, s84, v154
	v_readlane_b32 s88, v128, 40
	v_readlane_b32 s77, v130, 40
	v_readlane_b32 s78, v132, 40
	v_readlane_b32 s79, v134, 40
	v_readlane_b32 s80, v136, 40
	v_readlane_b32 s81, v138, 40
	v_readlane_b32 s82, v140, 40
	v_readlane_b32 s83, v142, 40
	v_readlane_b32 s84, v144, 40
	v_mul_f32_e32 v154, s88, v40
	v_fmac_f32_e32 v146, s77, v154
	v_fmac_f32_e32 v147, s78, v154
	v_fmac_f32_e32 v148, s79, v154
	v_fmac_f32_e32 v149, s80, v154
; __global__ void __launch_bounds__(NTHR, 2) hybrid_fwd(Args args) {
;     ...
;             for (int d = 0; d < 128; ++d) { const float wv = w_pool_out[(size_t)(gb + d) * 1024 + n] * pool_scale[gb + d];
; #pragma unroll
;                 for (int kk = 0; kk < 8; ++kk) a[kk] += pool_w[(size_t)(k0 + kk) * 128 + d] * wv; }
	v_fmac_f32_e32 v150, s81, v154
	v_fmac_f32_e32 v151, s82, v154
	v_fmac_f32_e32 v152, s83, v154
	v_fmac_f32_e32 v153, s84, v154
	v_readlane_b32 s88, v128, 41
	v_readlane_b32 s77, v130, 41
	v_readlane_b32 s78, v132, 41
	v_readlane_b32 s79, v134, 41
	v_readlane_b32 s80, v136, 41
	v_readlane_b32 s81, v138, 41
	v_readlane_b32 s82, v140, 41
	v_readlane_b32 s83, v142, 41
	v_readlane_b32 s84, v144, 41
	v_mul_f32_e32 v154, s88, v41
	v_fmac_f32_e32 v146, s77, v154
	v_fmac_f32_e32 v147, s78, v154
	v_fmac_f32_e32 v148, s79, v154
	v_fmac_f32_e32 v149, s80, v154
	v_fmac_f32_e32 v150, s81, v154
	v_fmac_f32_e32 v151, s82, v154
	v_fmac_f32_e32 v152, s83, v154
	v_fmac_f32_e32 v153, s84, v154
	v_readlane_b32 s88, v128, 42
	v_readlane_b32 s77, v130, 42
	v_readlane_b32 s78, v132, 42
	v_readlane_b32 s79, v134, 42
	v_readlane_b32 s80, v136, 42
	v_readlane_b32 s81, v138, 42
	v_readlane_b32 s82, v140, 42
	v_readlane_b32 s83, v142, 42
	v_readlane_b32 s84, v144, 42
	v_mul_f32_e32 v154, s88, v42
	v_fmac_f32_e32 v146, s77, v154
	v_fmac_f32_e32 v147, s78, v154
	v_fmac_f32_e32 v148, s79, v154
	v_fmac_f32_e32 v149, s80, v154
	v_fmac_f32_e32 v150, s81, v154
	v_fmac_f32_e32 v151, s82, v154
	v_fmac_f32_e32 v152, s83, v154
	v_fmac_f32_e32 v153, s84, v154
	v_readlane_b32 s88, v128, 43
	v_readlane_b32 s77, v130, 43
	v_readlane_b32 s78, v132, 43
	v_readlane_b32 s79, v134, 43
	v_readlane_b32 s80, v136, 43
	v_readlane_b32 s81, v138, 43
	v_readlane_b32 s82, v140, 43
	v_readlane_b32 s83, v142, 43
	v_readlane_b32 s84, v144, 43
	v_mul_f32_e32 v154, s88, v43
	v_fmac_f32_e32 v146, s77, v154
	v_fmac_f32_e32 v147, s78, v154
	v_fmac_f32_e32 v148, s79, v154
	v_fmac_f32_e32 v149, s80, v154
	v_fmac_f32_e32 v150, s81, v154
	v_fmac_f32_e32 v151, s82, v154
	v_fmac_f32_e32 v152, s83, v154
	v_fmac_f32_e32 v153, s84, v154
	v_readlane_b32 s88, v128, 44
	v_readlane_b32 s77, v130, 44
	v_readlane_b32 s78, v132, 44
	v_readlane_b32 s79, v134, 44
	v_readlane_b32 s80, v136, 44
	v_readlane_b32 s81, v138, 44
	v_readlane_b32 s82, v140, 44
	v_readlane_b32 s83, v142, 44
	v_readlane_b32 s84, v144, 44
	v_mul_f32_e32 v154, s88, v44
	v_fmac_f32_e32 v146, s77, v154
	v_fmac_f32_e32 v147, s78, v154
	v_fmac_f32_e32 v148, s79, v154
	v_fmac_f32_e32 v149, s80, v154
	v_fmac_f32_e32 v150, s81, v154
	v_fmac_f32_e32 v151, s82, v154
	v_fmac_f32_e32 v152, s83, v154
	v_fmac_f32_e32 v153, s84, v154
	v_readlane_b32 s88, v128, 45
	v_readlane_b32 s77, v130, 45
	v_readlane_b32 s78, v132, 45
	v_readlane_b32 s79, v134, 45
	v_readlane_b32 s80, v136, 45
	v_readlane_b32 s81, v138, 45
	v_readlane_b32 s82, v140, 45
	v_readlane_b32 s83, v142, 45
	v_readlane_b32 s84, v144, 45
	v_mul_f32_e32 v154, s88, v45
	v_fmac_f32_e32 v146, s77, v154
	v_fmac_f32_e32 v147, s78, v154
	v_fmac_f32_e32 v148, s79, v154
	v_fmac_f32_e32 v149, s80, v154
	v_fmac_f32_e32 v150, s81, v154
	v_fmac_f32_e32 v151, s82, v154
	v_fmac_f32_e32 v152, s83, v154
	v_fmac_f32_e32 v153, s84, v154
	v_readlane_b32 s88, v128, 46
	v_readlane_b32 s77, v130, 46
	v_readlane_b32 s78, v132, 46
	v_readlane_b32 s79, v134, 46
	v_readlane_b32 s80, v136, 46
	v_readlane_b32 s81, v138, 46
	v_readlane_b32 s82, v140, 46
	v_readlane_b32 s83, v142, 46
	v_readlane_b32 s84, v144, 46
	v_mul_f32_e32 v154, s88, v46
	v_fmac_f32_e32 v146, s77, v154
	v_fmac_f32_e32 v147, s78, v154
	v_fmac_f32_e32 v148, s79, v154
	v_fmac_f32_e32 v149, s80, v154
	v_fmac_f32_e32 v150, s81, v154
	v_fmac_f32_e32 v151, s82, v154
	v_fmac_f32_e32 v152, s83, v154
	v_fmac_f32_e32 v153, s84, v154
	v_readlane_b32 s88, v128, 47
	v_readlane_b32 s77, v130, 47
	v_readlane_b32 s78, v132, 47
	v_readlane_b32 s79, v134, 47
	v_readlane_b32 s80, v136, 47
	v_readlane_b32 s81, v138, 47
	v_readlane_b32 s82, v140, 47
	v_readlane_b32 s83, v142, 47
	v_readlane_b32 s84, v144, 47
	v_mul_f32_e32 v154, s88, v47
	v_fmac_f32_e32 v146, s77, v154
	v_fmac_f32_e32 v147, s78, v154
	v_fmac_f32_e32 v148, s79, v154
	v_fmac_f32_e32 v149, s80, v154
	v_fmac_f32_e32 v150, s81, v154
	v_fmac_f32_e32 v151, s82, v154
	v_fmac_f32_e32 v152, s83, v154
	v_fmac_f32_e32 v153, s84, v154
	v_readlane_b32 s88, v128, 48
	v_readlane_b32 s77, v130, 48
	v_readlane_b32 s78, v132, 48
	v_readlane_b32 s79, v134, 48
	v_readlane_b32 s80, v136, 48
	v_readlane_b32 s81, v138, 48
	v_readlane_b32 s82, v140, 48
	v_readlane_b32 s83, v142, 48
	v_readlane_b32 s84, v144, 48
	v_mul_f32_e32 v154, s88, v48
	v_fmac_f32_e32 v146, s77, v154
	v_fmac_f32_e32 v147, s78, v154
	v_fmac_f32_e32 v148, s79, v154
	v_fmac_f32_e32 v149, s80, v154
	v_fmac_f32_e32 v150, s81, v154
	v_fmac_f32_e32 v151, s82, v154
	v_fmac_f32_e32 v152, s83, v154
	v_fmac_f32_e32 v153, s84, v154
	v_readlane_b32 s88, v128, 49
	v_readlane_b32 s77, v130, 49
	v_readlane_b32 s78, v132, 49
	v_readlane_b32 s79, v134, 49
	v_readlane_b32 s80, v136, 49
	v_readlane_b32 s81, v138, 49
	v_readlane_b32 s82, v140, 49
	v_readlane_b32 s83, v142, 49
	v_readlane_b32 s84, v144, 49
	v_mul_f32_e32 v154, s88, v49
	v_fmac_f32_e32 v146, s77, v154
	v_fmac_f32_e32 v147, s78, v154
	v_fmac_f32_e32 v148, s79, v154
	v_fmac_f32_e32 v149, s80, v154
	v_fmac_f32_e32 v150, s81, v154
	v_fmac_f32_e32 v151, s82, v154
	v_fmac_f32_e32 v152, s83, v154
	v_fmac_f32_e32 v153, s84, v154
	v_readlane_b32 s88, v128, 50
	v_readlane_b32 s77, v130, 50
	v_readlane_b32 s78, v132, 50
	v_readlane_b32 s79, v134, 50
	v_readlane_b32 s80, v136, 50
	v_readlane_b32 s81, v138, 50
	v_readlane_b32 s82, v140, 50
	v_readlane_b32 s83, v142, 50
	v_readlane_b32 s84, v144, 50
	v_mul_f32_e32 v154, s88, v50
	v_fmac_f32_e32 v146, s77, v154
	v_fmac_f32_e32 v147, s78, v154
	v_fmac_f32_e32 v148, s79, v154
	v_fmac_f32_e32 v149, s80, v154
	v_fmac_f32_e32 v150, s81, v154
	v_fmac_f32_e32 v151, s82, v154
; __global__ void __launch_bounds__(NTHR, 2) hybrid_fwd(Args args) {
;     ...
;             for (int d = 0; d < 128; ++d) { const float wv = w_pool_out[(size_t)(gb + d) * 1024 + n] * pool_scale[gb + d];
; #pragma unroll
;                 for (int kk = 0; kk < 8; ++kk) a[kk] += pool_w[(size_t)(k0 + kk) * 128 + d] * wv; }
	v_fmac_f32_e32 v152, s83, v154
	v_fmac_f32_e32 v153, s84, v154
	v_readlane_b32 s88, v128, 51
	v_readlane_b32 s77, v130, 51
	v_readlane_b32 s78, v132, 51
	v_readlane_b32 s79, v134, 51
	v_readlane_b32 s80, v136, 51
	v_readlane_b32 s81, v138, 51
	v_readlane_b32 s82, v140, 51
	v_readlane_b32 s83, v142, 51
	v_readlane_b32 s84, v144, 51
	v_mul_f32_e32 v154, s88, v51
	v_fmac_f32_e32 v146, s77, v154
	v_fmac_f32_e32 v147, s78, v154
	v_fmac_f32_e32 v148, s79, v154
	v_fmac_f32_e32 v149, s80, v154
	v_fmac_f32_e32 v150, s81, v154
	v_fmac_f32_e32 v151, s82, v154
	v_fmac_f32_e32 v152, s83, v154
	v_fmac_f32_e32 v153, s84, v154
	v_readlane_b32 s88, v128, 52
	v_readlane_b32 s77, v130, 52
	v_readlane_b32 s78, v132, 52
	v_readlane_b32 s79, v134, 52
	v_readlane_b32 s80, v136, 52
	v_readlane_b32 s81, v138, 52
	v_readlane_b32 s82, v140, 52
	v_readlane_b32 s83, v142, 52
	v_readlane_b32 s84, v144, 52
	v_mul_f32_e32 v154, s88, v52
	v_fmac_f32_e32 v146, s77, v154
	v_fmac_f32_e32 v147, s78, v154
	v_fmac_f32_e32 v148, s79, v154
	v_fmac_f32_e32 v149, s80, v154
	v_fmac_f32_e32 v150, s81, v154
	v_fmac_f32_e32 v151, s82, v154
	v_fmac_f32_e32 v152, s83, v154
	v_fmac_f32_e32 v153, s84, v154
	v_readlane_b32 s88, v128, 53
	v_readlane_b32 s77, v130, 53
	v_readlane_b32 s78, v132, 53
	v_readlane_b32 s79, v134, 53
	v_readlane_b32 s80, v136, 53
	v_readlane_b32 s81, v138, 53
	v_readlane_b32 s82, v140, 53
	v_readlane_b32 s83, v142, 53
	v_readlane_b32 s84, v144, 53
	v_mul_f32_e32 v154, s88, v53
	v_fmac_f32_e32 v146, s77, v154
	v_fmac_f32_e32 v147, s78, v154
	v_fmac_f32_e32 v148, s79, v154
	v_fmac_f32_e32 v149, s80, v154
	v_fmac_f32_e32 v150, s81, v154
	v_fmac_f32_e32 v151, s82, v154
	v_fmac_f32_e32 v152, s83, v154
	v_fmac_f32_e32 v153, s84, v154
	v_readlane_b32 s88, v128, 54
	v_readlane_b32 s77, v130, 54
	v_readlane_b32 s78, v132, 54
	v_readlane_b32 s79, v134, 54
	v_readlane_b32 s80, v136, 54
	v_readlane_b32 s81, v138, 54
	v_readlane_b32 s82, v140, 54
	v_readlane_b32 s83, v142, 54
	v_readlane_b32 s84, v144, 54
	v_mul_f32_e32 v154, s88, v54
	v_fmac_f32_e32 v146, s77, v154
	v_fmac_f32_e32 v147, s78, v154
	v_fmac_f32_e32 v148, s79, v154
	v_fmac_f32_e32 v149, s80, v154
	v_fmac_f32_e32 v150, s81, v154
	v_fmac_f32_e32 v151, s82, v154
	v_fmac_f32_e32 v152, s83, v154
	v_fmac_f32_e32 v153, s84, v154
	v_readlane_b32 s88, v128, 55
	v_readlane_b32 s77, v130, 55
	v_readlane_b32 s78, v132, 55
	v_readlane_b32 s79, v134, 55
	v_readlane_b32 s80, v136, 55
	v_readlane_b32 s81, v138, 55
	v_readlane_b32 s82, v140, 55
	v_readlane_b32 s83, v142, 55
	v_readlane_b32 s84, v144, 55
	v_mul_f32_e32 v154, s88, v55
	v_fmac_f32_e32 v146, s77, v154
	v_fmac_f32_e32 v147, s78, v154
	v_fmac_f32_e32 v148, s79, v154
	v_fmac_f32_e32 v149, s80, v154
	v_fmac_f32_e32 v150, s81, v154
	v_fmac_f32_e32 v151, s82, v154
	v_fmac_f32_e32 v152, s83, v154
	v_fmac_f32_e32 v153, s84, v154
	v_readlane_b32 s88, v128, 56
	v_readlane_b32 s77, v130, 56
	v_readlane_b32 s78, v132, 56
	v_readlane_b32 s79, v134, 56
	v_readlane_b32 s80, v136, 56
	v_readlane_b32 s81, v138, 56
	v_readlane_b32 s82, v140, 56
	v_readlane_b32 s83, v142, 56
	v_readlane_b32 s84, v144, 56
	v_mul_f32_e32 v154, s88, v56
	v_fmac_f32_e32 v146, s77, v154
	v_fmac_f32_e32 v147, s78, v154
	v_fmac_f32_e32 v148, s79, v154
	v_fmac_f32_e32 v149, s80, v154
	v_fmac_f32_e32 v150, s81, v154
	v_fmac_f32_e32 v151, s82, v154
	v_fmac_f32_e32 v152, s83, v154
	v_fmac_f32_e32 v153, s84, v154
	v_readlane_b32 s88, v128, 57
	v_readlane_b32 s77, v130, 57
	v_readlane_b32 s78, v132, 57
	v_readlane_b32 s79, v134, 57
	v_readlane_b32 s80, v136, 57
	v_readlane_b32 s81, v138, 57
	v_readlane_b32 s82, v140, 57
	v_readlane_b32 s83, v142, 57
	v_readlane_b32 s84, v144, 57
	v_mul_f32_e32 v154, s88, v57
	v_fmac_f32_e32 v146, s77, v154
	v_fmac_f32_e32 v147, s78, v154
	v_fmac_f32_e32 v148, s79, v154
	v_fmac_f32_e32 v149, s80, v154
	v_fmac_f32_e32 v150, s81, v154
	v_fmac_f32_e32 v151, s82, v154
	v_fmac_f32_e32 v152, s83, v154
	v_fmac_f32_e32 v153, s84, v154
	v_readlane_b32 s88, v128, 58
	v_readlane_b32 s77, v130, 58
	v_readlane_b32 s78, v132, 58
	v_readlane_b32 s79, v134, 58
	v_readlane_b32 s80, v136, 58
	v_readlane_b32 s81, v138, 58
	v_readlane_b32 s82, v140, 58
	v_readlane_b32 s83, v142, 58
	v_readlane_b32 s84, v144, 58
	v_mul_f32_e32 v154, s88, v58
	v_fmac_f32_e32 v146, s77, v154
	v_fmac_f32_e32 v147, s78, v154
	v_fmac_f32_e32 v148, s79, v154
	v_fmac_f32_e32 v149, s80, v154
	v_fmac_f32_e32 v150, s81, v154
	v_fmac_f32_e32 v151, s82, v154
	v_fmac_f32_e32 v152, s83, v154
	v_fmac_f32_e32 v153, s84, v154
	v_readlane_b32 s88, v128, 59
	v_readlane_b32 s77, v130, 59
	v_readlane_b32 s78, v132, 59
	v_readlane_b32 s79, v134, 59
	v_readlane_b32 s80, v136, 59
	v_readlane_b32 s81, v138, 59
	v_readlane_b32 s82, v140, 59
	v_readlane_b32 s83, v142, 59
	v_readlane_b32 s84, v144, 59
	v_mul_f32_e32 v154, s88, v59
	v_fmac_f32_e32 v146, s77, v154
	v_fmac_f32_e32 v147, s78, v154
	v_fmac_f32_e32 v148, s79, v154
	v_fmac_f32_e32 v149, s80, v154
	v_fmac_f32_e32 v150, s81, v154
	v_fmac_f32_e32 v151, s82, v154
	v_fmac_f32_e32 v152, s83, v154
	v_fmac_f32_e32 v153, s84, v154
	v_readlane_b32 s88, v128, 60
	v_readlane_b32 s77, v130, 60
	v_readlane_b32 s78, v132, 60
	v_readlane_b32 s79, v134, 60
	v_readlane_b32 s80, v136, 60
	v_readlane_b32 s81, v138, 60
	v_readlane_b32 s82, v140, 60
	v_readlane_b32 s83, v142, 60
	v_readlane_b32 s84, v144, 60
	v_mul_f32_e32 v154, s88, v60
	v_fmac_f32_e32 v146, s77, v154
	v_fmac_f32_e32 v147, s78, v154
	v_fmac_f32_e32 v148, s79, v154
	v_fmac_f32_e32 v149, s80, v154
	v_fmac_f32_e32 v150, s81, v154
	v_fmac_f32_e32 v151, s82, v154
	v_fmac_f32_e32 v152, s83, v154
	v_fmac_f32_e32 v153, s84, v154
	v_readlane_b32 s88, v128, 61
; __global__ void __launch_bounds__(NTHR, 2) hybrid_fwd(Args args) {
;     ...
;             for (int d = 0; d < 128; ++d) { const float wv = w_pool_out[(size_t)(gb + d) * 1024 + n] * pool_scale[gb + d];
; #pragma unroll
;                 for (int kk = 0; kk < 8; ++kk) a[kk] += pool_w[(size_t)(k0 + kk) * 128 + d] * wv; }
	v_readlane_b32 s77, v130, 61
	v_readlane_b32 s78, v132, 61
	v_readlane_b32 s79, v134, 61
	v_readlane_b32 s80, v136, 61
	v_readlane_b32 s81, v138, 61
	v_readlane_b32 s82, v140, 61
	v_readlane_b32 s83, v142, 61
	v_readlane_b32 s84, v144, 61
	v_mul_f32_e32 v154, s88, v61
	v_fmac_f32_e32 v146, s77, v154
	v_fmac_f32_e32 v147, s78, v154
	v_fmac_f32_e32 v148, s79, v154
	v_fmac_f32_e32 v149, s80, v154
	v_fmac_f32_e32 v150, s81, v154
	v_fmac_f32_e32 v151, s82, v154
	v_fmac_f32_e32 v152, s83, v154
	v_fmac_f32_e32 v153, s84, v154
	v_readlane_b32 s88, v128, 62
	v_readlane_b32 s77, v130, 62
	v_readlane_b32 s78, v132, 62
	v_readlane_b32 s79, v134, 62
	v_readlane_b32 s80, v136, 62
	v_readlane_b32 s81, v138, 62
	v_readlane_b32 s82, v140, 62
	v_readlane_b32 s83, v142, 62
	v_readlane_b32 s84, v144, 62
	v_mul_f32_e32 v154, s88, v62
	v_fmac_f32_e32 v146, s77, v154
	v_fmac_f32_e32 v147, s78, v154
	v_fmac_f32_e32 v148, s79, v154
	v_fmac_f32_e32 v149, s80, v154
	v_fmac_f32_e32 v150, s81, v154
	v_fmac_f32_e32 v151, s82, v154
	v_fmac_f32_e32 v152, s83, v154
	v_fmac_f32_e32 v153, s84, v154
	v_readlane_b32 s88, v128, 63
	v_readlane_b32 s77, v130, 63
	v_readlane_b32 s78, v132, 63
	v_readlane_b32 s79, v134, 63
	v_readlane_b32 s80, v136, 63
	v_readlane_b32 s81, v138, 63
	v_readlane_b32 s82, v140, 63
	v_readlane_b32 s83, v142, 63
	v_readlane_b32 s84, v144, 63
	v_mul_f32_e32 v154, s88, v63
	v_fmac_f32_e32 v146, s77, v154
	v_fmac_f32_e32 v147, s78, v154
	v_fmac_f32_e32 v148, s79, v154
	v_fmac_f32_e32 v149, s80, v154
	v_fmac_f32_e32 v150, s81, v154
	v_fmac_f32_e32 v151, s82, v154
	v_fmac_f32_e32 v152, s83, v154
	v_fmac_f32_e32 v153, s84, v154
	v_readlane_b32 s88, v129, 0
	v_readlane_b32 s77, v131, 0
	v_readlane_b32 s78, v133, 0
	v_readlane_b32 s79, v135, 0
	v_readlane_b32 s80, v137, 0
	v_readlane_b32 s81, v139, 0
	v_readlane_b32 s82, v141, 0
	v_readlane_b32 s83, v143, 0
	v_readlane_b32 s84, v145, 0
	v_mul_f32_e32 v154, s88, v64
	v_fmac_f32_e32 v146, s77, v154
	v_fmac_f32_e32 v147, s78, v154
	v_fmac_f32_e32 v148, s79, v154
	v_fmac_f32_e32 v149, s80, v154
	v_fmac_f32_e32 v150, s81, v154
	v_fmac_f32_e32 v151, s82, v154
	v_fmac_f32_e32 v152, s83, v154
	v_fmac_f32_e32 v153, s84, v154
	v_readlane_b32 s88, v129, 1
	v_readlane_b32 s77, v131, 1
	v_readlane_b32 s78, v133, 1
	v_readlane_b32 s79, v135, 1
	v_readlane_b32 s80, v137, 1
	v_readlane_b32 s81, v139, 1
	v_readlane_b32 s82, v141, 1
	v_readlane_b32 s83, v143, 1
	v_readlane_b32 s84, v145, 1
	v_mul_f32_e32 v154, s88, v65
	v_fmac_f32_e32 v146, s77, v154
	v_fmac_f32_e32 v147, s78, v154
	v_fmac_f32_e32 v148, s79, v154
	v_fmac_f32_e32 v149, s80, v154
	v_fmac_f32_e32 v150, s81, v154
	v_fmac_f32_e32 v151, s82, v154
	v_fmac_f32_e32 v152, s83, v154
	v_fmac_f32_e32 v153, s84, v154
	v_readlane_b32 s88, v129, 2
	v_readlane_b32 s77, v131, 2
	v_readlane_b32 s78, v133, 2
	v_readlane_b32 s79, v135, 2
	v_readlane_b32 s80, v137, 2
	v_readlane_b32 s81, v139, 2
	v_readlane_b32 s82, v141, 2
	v_readlane_b32 s83, v143, 2
	v_readlane_b32 s84, v145, 2
	v_mul_f32_e32 v154, s88, v66
	v_fmac_f32_e32 v146, s77, v154
	v_fmac_f32_e32 v147, s78, v154
	v_fmac_f32_e32 v148, s79, v154
	v_fmac_f32_e32 v149, s80, v154
	v_fmac_f32_e32 v150, s81, v154
	v_fmac_f32_e32 v151, s82, v154
	v_fmac_f32_e32 v152, s83, v154
	v_fmac_f32_e32 v153, s84, v154
	v_readlane_b32 s88, v129, 3
	v_readlane_b32 s77, v131, 3
	v_readlane_b32 s78, v133, 3
	v_readlane_b32 s79, v135, 3
	v_readlane_b32 s80, v137, 3
	v_readlane_b32 s81, v139, 3
	v_readlane_b32 s82, v141, 3
	v_readlane_b32 s83, v143, 3
	v_readlane_b32 s84, v145, 3
	v_mul_f32_e32 v154, s88, v67
	v_fmac_f32_e32 v146, s77, v154
	v_fmac_f32_e32 v147, s78, v154
	v_fmac_f32_e32 v148, s79, v154
	v_fmac_f32_e32 v149, s80, v154
	v_fmac_f32_e32 v150, s81, v154
	v_fmac_f32_e32 v151, s82, v154
	v_fmac_f32_e32 v152, s83, v154
	v_fmac_f32_e32 v153, s84, v154
	v_readlane_b32 s88, v129, 4
	v_readlane_b32 s77, v131, 4
	v_readlane_b32 s78, v133, 4
	v_readlane_b32 s79, v135, 4
	v_readlane_b32 s80, v137, 4
	v_readlane_b32 s81, v139, 4
	v_readlane_b32 s82, v141, 4
	v_readlane_b32 s83, v143, 4
	v_readlane_b32 s84, v145, 4
	v_mul_f32_e32 v154, s88, v68
	v_fmac_f32_e32 v146, s77, v154
	v_fmac_f32_e32 v147, s78, v154
	v_fmac_f32_e32 v148, s79, v154
	v_fmac_f32_e32 v149, s80, v154
	v_fmac_f32_e32 v150, s81, v154
	v_fmac_f32_e32 v151, s82, v154
	v_fmac_f32_e32 v152, s83, v154
	v_fmac_f32_e32 v153, s84, v154
	v_readlane_b32 s88, v129, 5
	v_readlane_b32 s77, v131, 5
	v_readlane_b32 s78, v133, 5
	v_readlane_b32 s79, v135, 5
	v_readlane_b32 s80, v137, 5
	v_readlane_b32 s81, v139, 5
	v_readlane_b32 s82, v141, 5
	v_readlane_b32 s83, v143, 5
	v_readlane_b32 s84, v145, 5
	v_mul_f32_e32 v154, s88, v69
	v_fmac_f32_e32 v146, s77, v154
	v_fmac_f32_e32 v147, s78, v154
	v_fmac_f32_e32 v148, s79, v154
	v_fmac_f32_e32 v149, s80, v154
	v_fmac_f32_e32 v150, s81, v154
	v_fmac_f32_e32 v151, s82, v154
	v_fmac_f32_e32 v152, s83, v154
	v_fmac_f32_e32 v153, s84, v154
	v_readlane_b32 s88, v129, 6
	v_readlane_b32 s77, v131, 6
	v_readlane_b32 s78, v133, 6
	v_readlane_b32 s79, v135, 6
	v_readlane_b32 s80, v137, 6
	v_readlane_b32 s81, v139, 6
	v_readlane_b32 s82, v141, 6
	v_readlane_b32 s83, v143, 6
	v_readlane_b32 s84, v145, 6
	v_mul_f32_e32 v154, s88, v70
	v_fmac_f32_e32 v146, s77, v154
	v_fmac_f32_e32 v147, s78, v154
	v_fmac_f32_e32 v148, s79, v154
	v_fmac_f32_e32 v149, s80, v154
	v_fmac_f32_e32 v150, s81, v154
	v_fmac_f32_e32 v151, s82, v154
	v_fmac_f32_e32 v152, s83, v154
	v_fmac_f32_e32 v153, s84, v154
	v_readlane_b32 s88, v129, 7
	v_readlane_b32 s77, v131, 7
	v_readlane_b32 s78, v133, 7
	v_readlane_b32 s79, v135, 7
	v_readlane_b32 s80, v137, 7
	v_readlane_b32 s81, v139, 7
; __global__ void __launch_bounds__(NTHR, 2) hybrid_fwd(Args args) {
;     ...
;             for (int d = 0; d < 128; ++d) { const float wv = w_pool_out[(size_t)(gb + d) * 1024 + n] * pool_scale[gb + d];
; #pragma unroll
;                 for (int kk = 0; kk < 8; ++kk) a[kk] += pool_w[(size_t)(k0 + kk) * 128 + d] * wv; }
	v_readlane_b32 s82, v141, 7
	v_readlane_b32 s83, v143, 7
	v_readlane_b32 s84, v145, 7
	v_mul_f32_e32 v154, s88, v71
	v_fmac_f32_e32 v146, s77, v154
	v_fmac_f32_e32 v147, s78, v154
	v_fmac_f32_e32 v148, s79, v154
	v_fmac_f32_e32 v149, s80, v154
	v_fmac_f32_e32 v150, s81, v154
	v_fmac_f32_e32 v151, s82, v154
	v_fmac_f32_e32 v152, s83, v154
	v_fmac_f32_e32 v153, s84, v154
	v_readlane_b32 s88, v129, 8
	v_readlane_b32 s77, v131, 8
	v_readlane_b32 s78, v133, 8
	v_readlane_b32 s79, v135, 8
	v_readlane_b32 s80, v137, 8
	v_readlane_b32 s81, v139, 8
	v_readlane_b32 s82, v141, 8
	v_readlane_b32 s83, v143, 8
	v_readlane_b32 s84, v145, 8
	v_mul_f32_e32 v154, s88, v72
	v_fmac_f32_e32 v146, s77, v154
	v_fmac_f32_e32 v147, s78, v154
	v_fmac_f32_e32 v148, s79, v154
	v_fmac_f32_e32 v149, s80, v154
	v_fmac_f32_e32 v150, s81, v154
	v_fmac_f32_e32 v151, s82, v154
	v_fmac_f32_e32 v152, s83, v154
	v_fmac_f32_e32 v153, s84, v154
	v_readlane_b32 s88, v129, 9
	v_readlane_b32 s77, v131, 9
	v_readlane_b32 s78, v133, 9
	v_readlane_b32 s79, v135, 9
	v_readlane_b32 s80, v137, 9
	v_readlane_b32 s81, v139, 9
	v_readlane_b32 s82, v141, 9
	v_readlane_b32 s83, v143, 9
	v_readlane_b32 s84, v145, 9
	v_mul_f32_e32 v154, s88, v73
	v_fmac_f32_e32 v146, s77, v154
	v_fmac_f32_e32 v147, s78, v154
	v_fmac_f32_e32 v148, s79, v154
	v_fmac_f32_e32 v149, s80, v154
	v_fmac_f32_e32 v150, s81, v154
	v_fmac_f32_e32 v151, s82, v154
	v_fmac_f32_e32 v152, s83, v154
	v_fmac_f32_e32 v153, s84, v154
	v_readlane_b32 s88, v129, 10
	v_readlane_b32 s77, v131, 10
	v_readlane_b32 s78, v133, 10
	v_readlane_b32 s79, v135, 10
	v_readlane_b32 s80, v137, 10
	v_readlane_b32 s81, v139, 10
	v_readlane_b32 s82, v141, 10
	v_readlane_b32 s83, v143, 10
	v_readlane_b32 s84, v145, 10
	v_mul_f32_e32 v154, s88, v74
	v_fmac_f32_e32 v146, s77, v154
	v_fmac_f32_e32 v147, s78, v154
	v_fmac_f32_e32 v148, s79, v154
	v_fmac_f32_e32 v149, s80, v154
	v_fmac_f32_e32 v150, s81, v154
	v_fmac_f32_e32 v151, s82, v154
	v_fmac_f32_e32 v152, s83, v154
	v_fmac_f32_e32 v153, s84, v154
	v_readlane_b32 s88, v129, 11
	v_readlane_b32 s77, v131, 11
	v_readlane_b32 s78, v133, 11
	v_readlane_b32 s79, v135, 11
	v_readlane_b32 s80, v137, 11
	v_readlane_b32 s81, v139, 11
	v_readlane_b32 s82, v141, 11
	v_readlane_b32 s83, v143, 11
	v_readlane_b32 s84, v145, 11
	v_mul_f32_e32 v154, s88, v75
	v_fmac_f32_e32 v146, s77, v154
	v_fmac_f32_e32 v147, s78, v154
	v_fmac_f32_e32 v148, s79, v154
	v_fmac_f32_e32 v149, s80, v154
	v_fmac_f32_e32 v150, s81, v154
	v_fmac_f32_e32 v151, s82, v154
	v_fmac_f32_e32 v152, s83, v154
	v_fmac_f32_e32 v153, s84, v154
	v_readlane_b32 s88, v129, 12
	v_readlane_b32 s77, v131, 12
	v_readlane_b32 s78, v133, 12
	v_readlane_b32 s79, v135, 12
	v_readlane_b32 s80, v137, 12
	v_readlane_b32 s81, v139, 12
	v_readlane_b32 s82, v141, 12
	v_readlane_b32 s83, v143, 12
	v_readlane_b32 s84, v145, 12
	v_mul_f32_e32 v154, s88, v76
	v_fmac_f32_e32 v146, s77, v154
	v_fmac_f32_e32 v147, s78, v154
	v_fmac_f32_e32 v148, s79, v154
	v_fmac_f32_e32 v149, s80, v154
	v_fmac_f32_e32 v150, s81, v154
	v_fmac_f32_e32 v151, s82, v154
	v_fmac_f32_e32 v152, s83, v154
	v_fmac_f32_e32 v153, s84, v154
	v_readlane_b32 s88, v129, 13
	v_readlane_b32 s77, v131, 13
	v_readlane_b32 s78, v133, 13
	v_readlane_b32 s79, v135, 13
	v_readlane_b32 s80, v137, 13
	v_readlane_b32 s81, v139, 13
	v_readlane_b32 s82, v141, 13
	v_readlane_b32 s83, v143, 13
	v_readlane_b32 s84, v145, 13
	v_mul_f32_e32 v154, s88, v77
	v_fmac_f32_e32 v146, s77, v154
	v_fmac_f32_e32 v147, s78, v154
	v_fmac_f32_e32 v148, s79, v154
	v_fmac_f32_e32 v149, s80, v154
	v_fmac_f32_e32 v150, s81, v154
	v_fmac_f32_e32 v151, s82, v154
	v_fmac_f32_e32 v152, s83, v154
	v_fmac_f32_e32 v153, s84, v154
	v_readlane_b32 s88, v129, 14
	v_readlane_b32 s77, v131, 14
	v_readlane_b32 s78, v133, 14
	v_readlane_b32 s79, v135, 14
	v_readlane_b32 s80, v137, 14
	v_readlane_b32 s81, v139, 14
	v_readlane_b32 s82, v141, 14
	v_readlane_b32 s83, v143, 14
	v_readlane_b32 s84, v145, 14
	v_mul_f32_e32 v154, s88, v78
	v_fmac_f32_e32 v146, s77, v154
	v_fmac_f32_e32 v147, s78, v154
	v_fmac_f32_e32 v148, s79, v154
	v_fmac_f32_e32 v149, s80, v154
	v_fmac_f32_e32 v150, s81, v154
	v_fmac_f32_e32 v151, s82, v154
	v_fmac_f32_e32 v152, s83, v154
	v_fmac_f32_e32 v153, s84, v154
	v_readlane_b32 s88, v129, 15
	v_readlane_b32 s77, v131, 15
	v_readlane_b32 s78, v133, 15
	v_readlane_b32 s79, v135, 15
	v_readlane_b32 s80, v137, 15
	v_readlane_b32 s81, v139, 15
	v_readlane_b32 s82, v141, 15
	v_readlane_b32 s83, v143, 15
	v_readlane_b32 s84, v145, 15
	v_mul_f32_e32 v154, s88, v79
	v_fmac_f32_e32 v146, s77, v154
	v_fmac_f32_e32 v147, s78, v154
	v_fmac_f32_e32 v148, s79, v154
	v_fmac_f32_e32 v149, s80, v154
	v_fmac_f32_e32 v150, s81, v154
	v_fmac_f32_e32 v151, s82, v154
	v_fmac_f32_e32 v152, s83, v154
	v_fmac_f32_e32 v153, s84, v154
	v_readlane_b32 s88, v129, 16
	v_readlane_b32 s77, v131, 16
	v_readlane_b32 s78, v133, 16
	v_readlane_b32 s79, v135, 16
	v_readlane_b32 s80, v137, 16
	v_readlane_b32 s81, v139, 16
	v_readlane_b32 s82, v141, 16
	v_readlane_b32 s83, v143, 16
	v_readlane_b32 s84, v145, 16
	v_mul_f32_e32 v154, s88, v80
	v_fmac_f32_e32 v146, s77, v154
	v_fmac_f32_e32 v147, s78, v154
	v_fmac_f32_e32 v148, s79, v154
	v_fmac_f32_e32 v149, s80, v154
	v_fmac_f32_e32 v150, s81, v154
	v_fmac_f32_e32 v151, s82, v154
	v_fmac_f32_e32 v152, s83, v154
	v_fmac_f32_e32 v153, s84, v154
	v_readlane_b32 s88, v129, 17
	v_readlane_b32 s77, v131, 17
	v_readlane_b32 s78, v133, 17
	v_readlane_b32 s79, v135, 17
	v_readlane_b32 s80, v137, 17
	v_readlane_b32 s81, v139, 17
	v_readlane_b32 s82, v141, 17
	v_readlane_b32 s83, v143, 17
	v_readlane_b32 s84, v145, 17
; __global__ void __launch_bounds__(NTHR, 2) hybrid_fwd(Args args) {
;     ...
;             for (int d = 0; d < 128; ++d) { const float wv = w_pool_out[(size_t)(gb + d) * 1024 + n] * pool_scale[gb + d];
; #pragma unroll
;                 for (int kk = 0; kk < 8; ++kk) a[kk] += pool_w[(size_t)(k0 + kk) * 128 + d] * wv; }
	v_mul_f32_e32 v154, s88, v81
	v_fmac_f32_e32 v146, s77, v154
	v_fmac_f32_e32 v147, s78, v154
	v_fmac_f32_e32 v148, s79, v154
	v_fmac_f32_e32 v149, s80, v154
	v_fmac_f32_e32 v150, s81, v154
	v_fmac_f32_e32 v151, s82, v154
	v_fmac_f32_e32 v152, s83, v154
	v_fmac_f32_e32 v153, s84, v154
	v_readlane_b32 s88, v129, 18
	v_readlane_b32 s77, v131, 18
	v_readlane_b32 s78, v133, 18
	v_readlane_b32 s79, v135, 18
	v_readlane_b32 s80, v137, 18
	v_readlane_b32 s81, v139, 18
	v_readlane_b32 s82, v141, 18
	v_readlane_b32 s83, v143, 18
	v_readlane_b32 s84, v145, 18
	v_mul_f32_e32 v154, s88, v82
	v_fmac_f32_e32 v146, s77, v154
	v_fmac_f32_e32 v147, s78, v154
	v_fmac_f32_e32 v148, s79, v154
	v_fmac_f32_e32 v149, s80, v154
	v_fmac_f32_e32 v150, s81, v154
	v_fmac_f32_e32 v151, s82, v154
	v_fmac_f32_e32 v152, s83, v154
	v_fmac_f32_e32 v153, s84, v154
	v_readlane_b32 s88, v129, 19
	v_readlane_b32 s77, v131, 19
	v_readlane_b32 s78, v133, 19
	v_readlane_b32 s79, v135, 19
	v_readlane_b32 s80, v137, 19
	v_readlane_b32 s81, v139, 19
	v_readlane_b32 s82, v141, 19
	v_readlane_b32 s83, v143, 19
	v_readlane_b32 s84, v145, 19
	v_mul_f32_e32 v154, s88, v83
	v_fmac_f32_e32 v146, s77, v154
	v_fmac_f32_e32 v147, s78, v154
	v_fmac_f32_e32 v148, s79, v154
	v_fmac_f32_e32 v149, s80, v154
	v_fmac_f32_e32 v150, s81, v154
	v_fmac_f32_e32 v151, s82, v154
	v_fmac_f32_e32 v152, s83, v154
	v_fmac_f32_e32 v153, s84, v154
	v_readlane_b32 s88, v129, 20
	v_readlane_b32 s77, v131, 20
	v_readlane_b32 s78, v133, 20
	v_readlane_b32 s79, v135, 20
	v_readlane_b32 s80, v137, 20
	v_readlane_b32 s81, v139, 20
	v_readlane_b32 s82, v141, 20
	v_readlane_b32 s83, v143, 20
	v_readlane_b32 s84, v145, 20
	v_mul_f32_e32 v154, s88, v84
	v_fmac_f32_e32 v146, s77, v154
	v_fmac_f32_e32 v147, s78, v154
	v_fmac_f32_e32 v148, s79, v154
	v_fmac_f32_e32 v149, s80, v154
	v_fmac_f32_e32 v150, s81, v154
	v_fmac_f32_e32 v151, s82, v154
	v_fmac_f32_e32 v152, s83, v154
	v_fmac_f32_e32 v153, s84, v154
	v_readlane_b32 s88, v129, 21
	v_readlane_b32 s77, v131, 21
	v_readlane_b32 s78, v133, 21
	v_readlane_b32 s79, v135, 21
	v_readlane_b32 s80, v137, 21
	v_readlane_b32 s81, v139, 21
	v_readlane_b32 s82, v141, 21
	v_readlane_b32 s83, v143, 21
	v_readlane_b32 s84, v145, 21
	v_mul_f32_e32 v154, s88, v85
	v_fmac_f32_e32 v146, s77, v154
	v_fmac_f32_e32 v147, s78, v154
	v_fmac_f32_e32 v148, s79, v154
	v_fmac_f32_e32 v149, s80, v154
	v_fmac_f32_e32 v150, s81, v154
	v_fmac_f32_e32 v151, s82, v154
	v_fmac_f32_e32 v152, s83, v154
	v_fmac_f32_e32 v153, s84, v154
	v_readlane_b32 s88, v129, 22
	v_readlane_b32 s77, v131, 22
	v_readlane_b32 s78, v133, 22
	v_readlane_b32 s79, v135, 22
	v_readlane_b32 s80, v137, 22
	v_readlane_b32 s81, v139, 22
	v_readlane_b32 s82, v141, 22
	v_readlane_b32 s83, v143, 22
	v_readlane_b32 s84, v145, 22
	v_mul_f32_e32 v154, s88, v86
	v_fmac_f32_e32 v146, s77, v154
	v_fmac_f32_e32 v147, s78, v154
	v_fmac_f32_e32 v148, s79, v154
	v_fmac_f32_e32 v149, s80, v154
	v_fmac_f32_e32 v150, s81, v154
	v_fmac_f32_e32 v151, s82, v154
	v_fmac_f32_e32 v152, s83, v154
	v_fmac_f32_e32 v153, s84, v154
	v_readlane_b32 s88, v129, 23
	v_readlane_b32 s77, v131, 23
	v_readlane_b32 s78, v133, 23
	v_readlane_b32 s79, v135, 23
	v_readlane_b32 s80, v137, 23
	v_readlane_b32 s81, v139, 23
	v_readlane_b32 s82, v141, 23
	v_readlane_b32 s83, v143, 23
	v_readlane_b32 s84, v145, 23
	v_mul_f32_e32 v154, s88, v87
	v_fmac_f32_e32 v146, s77, v154
	v_fmac_f32_e32 v147, s78, v154
	v_fmac_f32_e32 v148, s79, v154
	v_fmac_f32_e32 v149, s80, v154
	v_fmac_f32_e32 v150, s81, v154
	v_fmac_f32_e32 v151, s82, v154
	v_fmac_f32_e32 v152, s83, v154
	v_fmac_f32_e32 v153, s84, v154
	v_readlane_b32 s88, v129, 24
	v_readlane_b32 s77, v131, 24
	v_readlane_b32 s78, v133, 24
	v_readlane_b32 s79, v135, 24
	v_readlane_b32 s80, v137, 24
	v_readlane_b32 s81, v139, 24
	v_readlane_b32 s82, v141, 24
	v_readlane_b32 s83, v143, 24
	v_readlane_b32 s84, v145, 24
	v_mul_f32_e32 v154, s88, v88
	v_fmac_f32_e32 v146, s77, v154
	v_fmac_f32_e32 v147, s78, v154
	v_fmac_f32_e32 v148, s79, v154
	v_fmac_f32_e32 v149, s80, v154
	v_fmac_f32_e32 v150, s81, v154
	v_fmac_f32_e32 v151, s82, v154
	v_fmac_f32_e32 v152, s83, v154
	v_fmac_f32_e32 v153, s84, v154
	v_readlane_b32 s88, v129, 25
	v_readlane_b32 s77, v131, 25
	v_readlane_b32 s78, v133, 25
	v_readlane_b32 s79, v135, 25
	v_readlane_b32 s80, v137, 25
	v_readlane_b32 s81, v139, 25
	v_readlane_b32 s82, v141, 25
	v_readlane_b32 s83, v143, 25
	v_readlane_b32 s84, v145, 25
	v_mul_f32_e32 v154, s88, v89
	v_fmac_f32_e32 v146, s77, v154
	v_fmac_f32_e32 v147, s78, v154
	v_fmac_f32_e32 v148, s79, v154
	v_fmac_f32_e32 v149, s80, v154
	v_fmac_f32_e32 v150, s81, v154
	v_fmac_f32_e32 v151, s82, v154
	v_fmac_f32_e32 v152, s83, v154
	v_fmac_f32_e32 v153, s84, v154
	v_readlane_b32 s88, v129, 26
	v_readlane_b32 s77, v131, 26
	v_readlane_b32 s78, v133, 26
	v_readlane_b32 s79, v135, 26
	v_readlane_b32 s80, v137, 26
	v_readlane_b32 s81, v139, 26
	v_readlane_b32 s82, v141, 26
	v_readlane_b32 s83, v143, 26
	v_readlane_b32 s84, v145, 26
	v_mul_f32_e32 v154, s88, v90
	v_fmac_f32_e32 v146, s77, v154
	v_fmac_f32_e32 v147, s78, v154
	v_fmac_f32_e32 v148, s79, v154
	v_fmac_f32_e32 v149, s80, v154
	v_fmac_f32_e32 v150, s81, v154
	v_fmac_f32_e32 v151, s82, v154
	v_fmac_f32_e32 v152, s83, v154
	v_fmac_f32_e32 v153, s84, v154
	v_readlane_b32 s88, v129, 27
	v_readlane_b32 s77, v131, 27
	v_readlane_b32 s78, v133, 27
	v_readlane_b32 s79, v135, 27
	v_readlane_b32 s80, v137, 27
	v_readlane_b32 s81, v139, 27
	v_readlane_b32 s82, v141, 27
	v_readlane_b32 s83, v143, 27
	v_readlane_b32 s84, v145, 27
	v_mul_f32_e32 v154, s88, v91
	v_fmac_f32_e32 v146, s77, v154
	v_fmac_f32_e32 v147, s78, v154
; __global__ void __launch_bounds__(NTHR, 2) hybrid_fwd(Args args) {
;     ...
;             for (int d = 0; d < 128; ++d) { const float wv = w_pool_out[(size_t)(gb + d) * 1024 + n] * pool_scale[gb + d];
; #pragma unroll
;                 for (int kk = 0; kk < 8; ++kk) a[kk] += pool_w[(size_t)(k0 + kk) * 128 + d] * wv; }
	v_fmac_f32_e32 v148, s79, v154
	v_fmac_f32_e32 v149, s80, v154
	v_fmac_f32_e32 v150, s81, v154
	v_fmac_f32_e32 v151, s82, v154
	v_fmac_f32_e32 v152, s83, v154
	v_fmac_f32_e32 v153, s84, v154
	v_readlane_b32 s88, v129, 28
	v_readlane_b32 s77, v131, 28
	v_readlane_b32 s78, v133, 28
	v_readlane_b32 s79, v135, 28
	v_readlane_b32 s80, v137, 28
	v_readlane_b32 s81, v139, 28
	v_readlane_b32 s82, v141, 28
	v_readlane_b32 s83, v143, 28
	v_readlane_b32 s84, v145, 28
	v_mul_f32_e32 v154, s88, v92
	v_fmac_f32_e32 v146, s77, v154
	v_fmac_f32_e32 v147, s78, v154
	v_fmac_f32_e32 v148, s79, v154
	v_fmac_f32_e32 v149, s80, v154
	v_fmac_f32_e32 v150, s81, v154
	v_fmac_f32_e32 v151, s82, v154
	v_fmac_f32_e32 v152, s83, v154
	v_fmac_f32_e32 v153, s84, v154
	v_readlane_b32 s88, v129, 29
	v_readlane_b32 s77, v131, 29
	v_readlane_b32 s78, v133, 29
	v_readlane_b32 s79, v135, 29
	v_readlane_b32 s80, v137, 29
	v_readlane_b32 s81, v139, 29
	v_readlane_b32 s82, v141, 29
	v_readlane_b32 s83, v143, 29
	v_readlane_b32 s84, v145, 29
	v_mul_f32_e32 v154, s88, v93
	v_fmac_f32_e32 v146, s77, v154
	v_fmac_f32_e32 v147, s78, v154
	v_fmac_f32_e32 v148, s79, v154
	v_fmac_f32_e32 v149, s80, v154
	v_fmac_f32_e32 v150, s81, v154
	v_fmac_f32_e32 v151, s82, v154
	v_fmac_f32_e32 v152, s83, v154
	v_fmac_f32_e32 v153, s84, v154
	v_readlane_b32 s88, v129, 30
	v_readlane_b32 s77, v131, 30
	v_readlane_b32 s78, v133, 30
	v_readlane_b32 s79, v135, 30
	v_readlane_b32 s80, v137, 30
	v_readlane_b32 s81, v139, 30
	v_readlane_b32 s82, v141, 30
	v_readlane_b32 s83, v143, 30
	v_readlane_b32 s84, v145, 30
	v_mul_f32_e32 v154, s88, v94
	v_fmac_f32_e32 v146, s77, v154
	v_fmac_f32_e32 v147, s78, v154
	v_fmac_f32_e32 v148, s79, v154
	v_fmac_f32_e32 v149, s80, v154
	v_fmac_f32_e32 v150, s81, v154
	v_fmac_f32_e32 v151, s82, v154
	v_fmac_f32_e32 v152, s83, v154
	v_fmac_f32_e32 v153, s84, v154
	v_readlane_b32 s88, v129, 31
	v_readlane_b32 s77, v131, 31
	v_readlane_b32 s78, v133, 31
	v_readlane_b32 s79, v135, 31
	v_readlane_b32 s80, v137, 31
	v_readlane_b32 s81, v139, 31
	v_readlane_b32 s82, v141, 31
	v_readlane_b32 s83, v143, 31
	v_readlane_b32 s84, v145, 31
	v_mul_f32_e32 v154, s88, v95
	v_fmac_f32_e32 v146, s77, v154
	v_fmac_f32_e32 v147, s78, v154
	v_fmac_f32_e32 v148, s79, v154
	v_fmac_f32_e32 v149, s80, v154
	v_fmac_f32_e32 v150, s81, v154
	v_fmac_f32_e32 v151, s82, v154
	v_fmac_f32_e32 v152, s83, v154
	v_fmac_f32_e32 v153, s84, v154
	v_readlane_b32 s88, v129, 32
	v_readlane_b32 s77, v131, 32
	v_readlane_b32 s78, v133, 32
	v_readlane_b32 s79, v135, 32
	v_readlane_b32 s80, v137, 32
	v_readlane_b32 s81, v139, 32
	v_readlane_b32 s82, v141, 32
	v_readlane_b32 s83, v143, 32
	v_readlane_b32 s84, v145, 32
	v_mul_f32_e32 v154, s88, v96
	v_fmac_f32_e32 v146, s77, v154
	v_fmac_f32_e32 v147, s78, v154
	v_fmac_f32_e32 v148, s79, v154
	v_fmac_f32_e32 v149, s80, v154
	v_fmac_f32_e32 v150, s81, v154
	v_fmac_f32_e32 v151, s82, v154
	v_fmac_f32_e32 v152, s83, v154
	v_fmac_f32_e32 v153, s84, v154
	v_readlane_b32 s88, v129, 33
	v_readlane_b32 s77, v131, 33
	v_readlane_b32 s78, v133, 33
	v_readlane_b32 s79, v135, 33
	v_readlane_b32 s80, v137, 33
	v_readlane_b32 s81, v139, 33
	v_readlane_b32 s82, v141, 33
	v_readlane_b32 s83, v143, 33
	v_readlane_b32 s84, v145, 33
	v_mul_f32_e32 v154, s88, v97
	v_fmac_f32_e32 v146, s77, v154
	v_fmac_f32_e32 v147, s78, v154
	v_fmac_f32_e32 v148, s79, v154
	v_fmac_f32_e32 v149, s80, v154
	v_fmac_f32_e32 v150, s81, v154
	v_fmac_f32_e32 v151, s82, v154
	v_fmac_f32_e32 v152, s83, v154
	v_fmac_f32_e32 v153, s84, v154
	v_readlane_b32 s88, v129, 34
	v_readlane_b32 s77, v131, 34
	v_readlane_b32 s78, v133, 34
	v_readlane_b32 s79, v135, 34
	v_readlane_b32 s80, v137, 34
	v_readlane_b32 s81, v139, 34
	v_readlane_b32 s82, v141, 34
	v_readlane_b32 s83, v143, 34
	v_readlane_b32 s84, v145, 34
	v_mul_f32_e32 v154, s88, v98
	v_fmac_f32_e32 v146, s77, v154
	v_fmac_f32_e32 v147, s78, v154
	v_fmac_f32_e32 v148, s79, v154
	v_fmac_f32_e32 v149, s80, v154
	v_fmac_f32_e32 v150, s81, v154
	v_fmac_f32_e32 v151, s82, v154
	v_fmac_f32_e32 v152, s83, v154
	v_fmac_f32_e32 v153, s84, v154
	v_readlane_b32 s88, v129, 35
	v_readlane_b32 s77, v131, 35
	v_readlane_b32 s78, v133, 35
	v_readlane_b32 s79, v135, 35
	v_readlane_b32 s80, v137, 35
	v_readlane_b32 s81, v139, 35
	v_readlane_b32 s82, v141, 35
	v_readlane_b32 s83, v143, 35
	v_readlane_b32 s84, v145, 35
	v_mul_f32_e32 v154, s88, v99
	v_fmac_f32_e32 v146, s77, v154
	v_fmac_f32_e32 v147, s78, v154
	v_fmac_f32_e32 v148, s79, v154
	v_fmac_f32_e32 v149, s80, v154
	v_fmac_f32_e32 v150, s81, v154
	v_fmac_f32_e32 v151, s82, v154
	v_fmac_f32_e32 v152, s83, v154
	v_fmac_f32_e32 v153, s84, v154
	v_readlane_b32 s88, v129, 36
	v_readlane_b32 s77, v131, 36
	v_readlane_b32 s78, v133, 36
	v_readlane_b32 s79, v135, 36
	v_readlane_b32 s80, v137, 36
	v_readlane_b32 s81, v139, 36
	v_readlane_b32 s82, v141, 36
	v_readlane_b32 s83, v143, 36
	v_readlane_b32 s84, v145, 36
	v_mul_f32_e32 v154, s88, v100
	v_fmac_f32_e32 v146, s77, v154
	v_fmac_f32_e32 v147, s78, v154
	v_fmac_f32_e32 v148, s79, v154
	v_fmac_f32_e32 v149, s80, v154
	v_fmac_f32_e32 v150, s81, v154
	v_fmac_f32_e32 v151, s82, v154
	v_fmac_f32_e32 v152, s83, v154
	v_fmac_f32_e32 v153, s84, v154
	v_readlane_b32 s88, v129, 37
	v_readlane_b32 s77, v131, 37
	v_readlane_b32 s78, v133, 37
	v_readlane_b32 s79, v135, 37
	v_readlane_b32 s80, v137, 37
	v_readlane_b32 s81, v139, 37
	v_readlane_b32 s82, v141, 37
	v_readlane_b32 s83, v143, 37
	v_readlane_b32 s84, v145, 37
	v_mul_f32_e32 v154, s88, v101
	v_fmac_f32_e32 v146, s77, v154
	v_fmac_f32_e32 v147, s78, v154
	v_fmac_f32_e32 v148, s79, v154
	v_fmac_f32_e32 v149, s80, v154
; __global__ void __launch_bounds__(NTHR, 2) hybrid_fwd(Args args) {
;     ...
;             for (int d = 0; d < 128; ++d) { const float wv = w_pool_out[(size_t)(gb + d) * 1024 + n] * pool_scale[gb + d];
; #pragma unroll
;                 for (int kk = 0; kk < 8; ++kk) a[kk] += pool_w[(size_t)(k0 + kk) * 128 + d] * wv; }
	v_fmac_f32_e32 v150, s81, v154
	v_fmac_f32_e32 v151, s82, v154
	v_fmac_f32_e32 v152, s83, v154
	v_fmac_f32_e32 v153, s84, v154
	v_readlane_b32 s88, v129, 38
	v_readlane_b32 s77, v131, 38
	v_readlane_b32 s78, v133, 38
	v_readlane_b32 s79, v135, 38
	v_readlane_b32 s80, v137, 38
	v_readlane_b32 s81, v139, 38
	v_readlane_b32 s82, v141, 38
	v_readlane_b32 s83, v143, 38
	v_readlane_b32 s84, v145, 38
	v_mul_f32_e32 v154, s88, v102
	v_fmac_f32_e32 v146, s77, v154
	v_fmac_f32_e32 v147, s78, v154
	v_fmac_f32_e32 v148, s79, v154
	v_fmac_f32_e32 v149, s80, v154
	v_fmac_f32_e32 v150, s81, v154
	v_fmac_f32_e32 v151, s82, v154
	v_fmac_f32_e32 v152, s83, v154
	v_fmac_f32_e32 v153, s84, v154
	v_readlane_b32 s88, v129, 39
	v_readlane_b32 s77, v131, 39
	v_readlane_b32 s78, v133, 39
	v_readlane_b32 s79, v135, 39
	v_readlane_b32 s80, v137, 39
	v_readlane_b32 s81, v139, 39
	v_readlane_b32 s82, v141, 39
	v_readlane_b32 s83, v143, 39
	v_readlane_b32 s84, v145, 39
	v_mul_f32_e32 v154, s88, v103
	v_fmac_f32_e32 v146, s77, v154
	v_fmac_f32_e32 v147, s78, v154
	v_fmac_f32_e32 v148, s79, v154
	v_fmac_f32_e32 v149, s80, v154
	v_fmac_f32_e32 v150, s81, v154
	v_fmac_f32_e32 v151, s82, v154
	v_fmac_f32_e32 v152, s83, v154
	v_fmac_f32_e32 v153, s84, v154
	v_readlane_b32 s88, v129, 40
	v_readlane_b32 s77, v131, 40
	v_readlane_b32 s78, v133, 40
	v_readlane_b32 s79, v135, 40
	v_readlane_b32 s80, v137, 40
	v_readlane_b32 s81, v139, 40
	v_readlane_b32 s82, v141, 40
	v_readlane_b32 s83, v143, 40
	v_readlane_b32 s84, v145, 40
	v_mul_f32_e32 v154, s88, v104
	v_fmac_f32_e32 v146, s77, v154
	v_fmac_f32_e32 v147, s78, v154
	v_fmac_f32_e32 v148, s79, v154
	v_fmac_f32_e32 v149, s80, v154
	v_fmac_f32_e32 v150, s81, v154
	v_fmac_f32_e32 v151, s82, v154
	v_fmac_f32_e32 v152, s83, v154
	v_fmac_f32_e32 v153, s84, v154
	v_readlane_b32 s88, v129, 41
	v_readlane_b32 s77, v131, 41
	v_readlane_b32 s78, v133, 41
	v_readlane_b32 s79, v135, 41
	v_readlane_b32 s80, v137, 41
	v_readlane_b32 s81, v139, 41
	v_readlane_b32 s82, v141, 41
	v_readlane_b32 s83, v143, 41
	v_readlane_b32 s84, v145, 41
	v_mul_f32_e32 v154, s88, v105
	v_fmac_f32_e32 v146, s77, v154
	v_fmac_f32_e32 v147, s78, v154
	v_fmac_f32_e32 v148, s79, v154
	v_fmac_f32_e32 v149, s80, v154
	v_fmac_f32_e32 v150, s81, v154
	v_fmac_f32_e32 v151, s82, v154
	v_fmac_f32_e32 v152, s83, v154
	v_fmac_f32_e32 v153, s84, v154
	v_readlane_b32 s88, v129, 42
	v_readlane_b32 s77, v131, 42
	v_readlane_b32 s78, v133, 42
	v_readlane_b32 s79, v135, 42
	v_readlane_b32 s80, v137, 42
	v_readlane_b32 s81, v139, 42
	v_readlane_b32 s82, v141, 42
	v_readlane_b32 s83, v143, 42
	v_readlane_b32 s84, v145, 42
	v_mul_f32_e32 v154, s88, v106
	v_fmac_f32_e32 v146, s77, v154
	v_fmac_f32_e32 v147, s78, v154
	v_fmac_f32_e32 v148, s79, v154
	v_fmac_f32_e32 v149, s80, v154
	v_fmac_f32_e32 v150, s81, v154
	v_fmac_f32_e32 v151, s82, v154
	v_fmac_f32_e32 v152, s83, v154
	v_fmac_f32_e32 v153, s84, v154
	v_readlane_b32 s88, v129, 43
	v_readlane_b32 s77, v131, 43
	v_readlane_b32 s78, v133, 43
	v_readlane_b32 s79, v135, 43
	v_readlane_b32 s80, v137, 43
	v_readlane_b32 s81, v139, 43
	v_readlane_b32 s82, v141, 43
	v_readlane_b32 s83, v143, 43
	v_readlane_b32 s84, v145, 43
	v_mul_f32_e32 v154, s88, v107
	v_fmac_f32_e32 v146, s77, v154
	v_fmac_f32_e32 v147, s78, v154
	v_fmac_f32_e32 v148, s79, v154
	v_fmac_f32_e32 v149, s80, v154
	v_fmac_f32_e32 v150, s81, v154
	v_fmac_f32_e32 v151, s82, v154
	v_fmac_f32_e32 v152, s83, v154
	v_fmac_f32_e32 v153, s84, v154
	v_readlane_b32 s88, v129, 44
	v_readlane_b32 s77, v131, 44
	v_readlane_b32 s78, v133, 44
	v_readlane_b32 s79, v135, 44
	v_readlane_b32 s80, v137, 44
	v_readlane_b32 s81, v139, 44
	v_readlane_b32 s82, v141, 44
	v_readlane_b32 s83, v143, 44
	v_readlane_b32 s84, v145, 44
	v_mul_f32_e32 v154, s88, v108
	v_fmac_f32_e32 v146, s77, v154
	v_fmac_f32_e32 v147, s78, v154
	v_fmac_f32_e32 v148, s79, v154
	v_fmac_f32_e32 v149, s80, v154
	v_fmac_f32_e32 v150, s81, v154
	v_fmac_f32_e32 v151, s82, v154
	v_fmac_f32_e32 v152, s83, v154
	v_fmac_f32_e32 v153, s84, v154
	v_readlane_b32 s88, v129, 45
	v_readlane_b32 s77, v131, 45
	v_readlane_b32 s78, v133, 45
	v_readlane_b32 s79, v135, 45
	v_readlane_b32 s80, v137, 45
	v_readlane_b32 s81, v139, 45
	v_readlane_b32 s82, v141, 45
	v_readlane_b32 s83, v143, 45
	v_readlane_b32 s84, v145, 45
	v_mul_f32_e32 v154, s88, v109
	v_fmac_f32_e32 v146, s77, v154
	v_fmac_f32_e32 v147, s78, v154
	v_fmac_f32_e32 v148, s79, v154
	v_fmac_f32_e32 v149, s80, v154
	v_fmac_f32_e32 v150, s81, v154
	v_fmac_f32_e32 v151, s82, v154
	v_fmac_f32_e32 v152, s83, v154
	v_fmac_f32_e32 v153, s84, v154
	v_readlane_b32 s88, v129, 46
	v_readlane_b32 s77, v131, 46
	v_readlane_b32 s78, v133, 46
	v_readlane_b32 s79, v135, 46
	v_readlane_b32 s80, v137, 46
	v_readlane_b32 s81, v139, 46
	v_readlane_b32 s82, v141, 46
	v_readlane_b32 s83, v143, 46
	v_readlane_b32 s84, v145, 46
	v_mul_f32_e32 v154, s88, v110
	v_fmac_f32_e32 v146, s77, v154
	v_fmac_f32_e32 v147, s78, v154
	v_fmac_f32_e32 v148, s79, v154
	v_fmac_f32_e32 v149, s80, v154
	v_fmac_f32_e32 v150, s81, v154
	v_fmac_f32_e32 v151, s82, v154
	v_fmac_f32_e32 v152, s83, v154
	v_fmac_f32_e32 v153, s84, v154
	v_readlane_b32 s88, v129, 47
	v_readlane_b32 s77, v131, 47
	v_readlane_b32 s78, v133, 47
	v_readlane_b32 s79, v135, 47
	v_readlane_b32 s80, v137, 47
	v_readlane_b32 s81, v139, 47
	v_readlane_b32 s82, v141, 47
	v_readlane_b32 s83, v143, 47
	v_readlane_b32 s84, v145, 47
	v_mul_f32_e32 v154, s88, v111
	v_fmac_f32_e32 v146, s77, v154
	v_fmac_f32_e32 v147, s78, v154
	v_fmac_f32_e32 v148, s79, v154
	v_fmac_f32_e32 v149, s80, v154
	v_fmac_f32_e32 v150, s81, v154
	v_fmac_f32_e32 v151, s82, v154
; __global__ void __launch_bounds__(NTHR, 2) hybrid_fwd(Args args) {
;     ...
;             for (int d = 0; d < 128; ++d) { const float wv = w_pool_out[(size_t)(gb + d) * 1024 + n] * pool_scale[gb + d];
; #pragma unroll
;                 for (int kk = 0; kk < 8; ++kk) a[kk] += pool_w[(size_t)(k0 + kk) * 128 + d] * wv; }
	v_fmac_f32_e32 v152, s83, v154
	v_fmac_f32_e32 v153, s84, v154
	v_readlane_b32 s88, v129, 48
	v_readlane_b32 s77, v131, 48
	v_readlane_b32 s78, v133, 48
	v_readlane_b32 s79, v135, 48
	v_readlane_b32 s80, v137, 48
	v_readlane_b32 s81, v139, 48
	v_readlane_b32 s82, v141, 48
	v_readlane_b32 s83, v143, 48
	v_readlane_b32 s84, v145, 48
	v_mul_f32_e32 v154, s88, v112
	v_fmac_f32_e32 v146, s77, v154
	v_fmac_f32_e32 v147, s78, v154
	v_fmac_f32_e32 v148, s79, v154
	v_fmac_f32_e32 v149, s80, v154
	v_fmac_f32_e32 v150, s81, v154
	v_fmac_f32_e32 v151, s82, v154
	v_fmac_f32_e32 v152, s83, v154
	v_fmac_f32_e32 v153, s84, v154
	v_readlane_b32 s88, v129, 49
	v_readlane_b32 s77, v131, 49
	v_readlane_b32 s78, v133, 49
	v_readlane_b32 s79, v135, 49
	v_readlane_b32 s80, v137, 49
	v_readlane_b32 s81, v139, 49
	v_readlane_b32 s82, v141, 49
	v_readlane_b32 s83, v143, 49
	v_readlane_b32 s84, v145, 49
	v_mul_f32_e32 v154, s88, v113
	v_fmac_f32_e32 v146, s77, v154
	v_fmac_f32_e32 v147, s78, v154
	v_fmac_f32_e32 v148, s79, v154
	v_fmac_f32_e32 v149, s80, v154
	v_fmac_f32_e32 v150, s81, v154
	v_fmac_f32_e32 v151, s82, v154
	v_fmac_f32_e32 v152, s83, v154
	v_fmac_f32_e32 v153, s84, v154
	v_readlane_b32 s88, v129, 50
	v_readlane_b32 s77, v131, 50
	v_readlane_b32 s78, v133, 50
	v_readlane_b32 s79, v135, 50
	v_readlane_b32 s80, v137, 50
	v_readlane_b32 s81, v139, 50
	v_readlane_b32 s82, v141, 50
	v_readlane_b32 s83, v143, 50
	v_readlane_b32 s84, v145, 50
	v_mul_f32_e32 v154, s88, v114
	v_fmac_f32_e32 v146, s77, v154
	v_fmac_f32_e32 v147, s78, v154
	v_fmac_f32_e32 v148, s79, v154
	v_fmac_f32_e32 v149, s80, v154
	v_fmac_f32_e32 v150, s81, v154
	v_fmac_f32_e32 v151, s82, v154
	v_fmac_f32_e32 v152, s83, v154
	v_fmac_f32_e32 v153, s84, v154
	v_readlane_b32 s88, v129, 51
	v_readlane_b32 s77, v131, 51
	v_readlane_b32 s78, v133, 51
	v_readlane_b32 s79, v135, 51
	v_readlane_b32 s80, v137, 51
	v_readlane_b32 s81, v139, 51
	v_readlane_b32 s82, v141, 51
	v_readlane_b32 s83, v143, 51
	v_readlane_b32 s84, v145, 51
	v_mul_f32_e32 v154, s88, v115
	v_fmac_f32_e32 v146, s77, v154
	v_fmac_f32_e32 v147, s78, v154
	v_fmac_f32_e32 v148, s79, v154
	v_fmac_f32_e32 v149, s80, v154
	v_fmac_f32_e32 v150, s81, v154
	v_fmac_f32_e32 v151, s82, v154
	v_fmac_f32_e32 v152, s83, v154
	v_fmac_f32_e32 v153, s84, v154
	v_readlane_b32 s88, v129, 52
	v_readlane_b32 s77, v131, 52
	v_readlane_b32 s78, v133, 52
	v_readlane_b32 s79, v135, 52
	v_readlane_b32 s80, v137, 52
	v_readlane_b32 s81, v139, 52
	v_readlane_b32 s82, v141, 52
	v_readlane_b32 s83, v143, 52
	v_readlane_b32 s84, v145, 52
	v_mul_f32_e32 v154, s88, v116
	v_fmac_f32_e32 v146, s77, v154
	v_fmac_f32_e32 v147, s78, v154
	v_fmac_f32_e32 v148, s79, v154
	v_fmac_f32_e32 v149, s80, v154
	v_fmac_f32_e32 v150, s81, v154
	v_fmac_f32_e32 v151, s82, v154
	v_fmac_f32_e32 v152, s83, v154
	v_fmac_f32_e32 v153, s84, v154
	v_readlane_b32 s88, v129, 53
	v_readlane_b32 s77, v131, 53
	v_readlane_b32 s78, v133, 53
	v_readlane_b32 s79, v135, 53
	v_readlane_b32 s80, v137, 53
	v_readlane_b32 s81, v139, 53
	v_readlane_b32 s82, v141, 53
	v_readlane_b32 s83, v143, 53
	v_readlane_b32 s84, v145, 53
	v_mul_f32_e32 v154, s88, v117
	v_fmac_f32_e32 v146, s77, v154
	v_fmac_f32_e32 v147, s78, v154
	v_fmac_f32_e32 v148, s79, v154
	v_fmac_f32_e32 v149, s80, v154
	v_fmac_f32_e32 v150, s81, v154
	v_fmac_f32_e32 v151, s82, v154
	v_fmac_f32_e32 v152, s83, v154
	v_fmac_f32_e32 v153, s84, v154
	v_readlane_b32 s88, v129, 54
	v_readlane_b32 s77, v131, 54
	v_readlane_b32 s78, v133, 54
	v_readlane_b32 s79, v135, 54
	v_readlane_b32 s80, v137, 54
	v_readlane_b32 s81, v139, 54
	v_readlane_b32 s82, v141, 54
	v_readlane_b32 s83, v143, 54
	v_readlane_b32 s84, v145, 54
	v_mul_f32_e32 v154, s88, v118
	v_fmac_f32_e32 v146, s77, v154
	v_fmac_f32_e32 v147, s78, v154
	v_fmac_f32_e32 v148, s79, v154
	v_fmac_f32_e32 v149, s80, v154
	v_fmac_f32_e32 v150, s81, v154
	v_fmac_f32_e32 v151, s82, v154
	v_fmac_f32_e32 v152, s83, v154
	v_fmac_f32_e32 v153, s84, v154
	v_readlane_b32 s88, v129, 55
	v_readlane_b32 s77, v131, 55
	v_readlane_b32 s78, v133, 55
	v_readlane_b32 s79, v135, 55
	v_readlane_b32 s80, v137, 55
	v_readlane_b32 s81, v139, 55
	v_readlane_b32 s82, v141, 55
	v_readlane_b32 s83, v143, 55
	v_readlane_b32 s84, v145, 55
	v_mul_f32_e32 v154, s88, v119
	v_fmac_f32_e32 v146, s77, v154
	v_fmac_f32_e32 v147, s78, v154
	v_fmac_f32_e32 v148, s79, v154
	v_fmac_f32_e32 v149, s80, v154
	v_fmac_f32_e32 v150, s81, v154
	v_fmac_f32_e32 v151, s82, v154
	v_fmac_f32_e32 v152, s83, v154
	v_fmac_f32_e32 v153, s84, v154
	v_readlane_b32 s88, v129, 56
	v_readlane_b32 s77, v131, 56
	v_readlane_b32 s78, v133, 56
	v_readlane_b32 s79, v135, 56
	v_readlane_b32 s80, v137, 56
	v_readlane_b32 s81, v139, 56
	v_readlane_b32 s82, v141, 56
	v_readlane_b32 s83, v143, 56
	v_readlane_b32 s84, v145, 56
	v_mul_f32_e32 v154, s88, v120
	v_fmac_f32_e32 v146, s77, v154
	v_fmac_f32_e32 v147, s78, v154
	v_fmac_f32_e32 v148, s79, v154
	v_fmac_f32_e32 v149, s80, v154
	v_fmac_f32_e32 v150, s81, v154
	v_fmac_f32_e32 v151, s82, v154
	v_fmac_f32_e32 v152, s83, v154
	v_fmac_f32_e32 v153, s84, v154
	v_readlane_b32 s88, v129, 57
; __device__ __forceinline__ unsigned pk2(float lo, float hi) { return pg8::cvt_pk_bf16(lo, hi); }
; __global__ void __launch_bounds__(NTHR, 2) hybrid_fwd(Args args) {
;     ...
;             for (int d = 0; d < 128; ++d) { const float wv = w_pool_out[(size_t)(gb + d) * 1024 + n] * pool_scale[gb + d];
; #pragma unroll
;                 for (int kk = 0; kk < 8; ++kk) a[kk] += pool_w[(size_t)(k0 + kk) * 128 + d] * wv; }
;             u32x4 o; o.x = pk2(a[0], a[1]); o.y = pk2(a[2], a[3]); o.z = pk2(a[4], a[5]); o.w = pk2(a[6], a[7]);
;             *(u32x4*)(Wmix + (size_t)n * 1024 + k0) = o; }
	v_readlane_b32 s77, v131, 57
	v_readlane_b32 s78, v133, 57
	v_readlane_b32 s79, v135, 57
	v_readlane_b32 s80, v137, 57
	v_readlane_b32 s81, v139, 57
	v_readlane_b32 s82, v141, 57
	v_readlane_b32 s83, v143, 57
	v_readlane_b32 s84, v145, 57
	v_mul_f32_e32 v154, s88, v121
	v_fmac_f32_e32 v146, s77, v154
	v_fmac_f32_e32 v147, s78, v154
	v_fmac_f32_e32 v148, s79, v154
	v_fmac_f32_e32 v149, s80, v154
	v_fmac_f32_e32 v150, s81, v154
	v_fmac_f32_e32 v151, s82, v154
	v_fmac_f32_e32 v152, s83, v154
	v_fmac_f32_e32 v153, s84, v154
	v_readlane_b32 s88, v129, 58
	v_readlane_b32 s77, v131, 58
	v_readlane_b32 s78, v133, 58
	v_readlane_b32 s79, v135, 58
	v_readlane_b32 s80, v137, 58
	v_readlane_b32 s81, v139, 58
	v_readlane_b32 s82, v141, 58
	v_readlane_b32 s83, v143, 58
	v_readlane_b32 s84, v145, 58
	v_mul_f32_e32 v154, s88, v122
	v_fmac_f32_e32 v146, s77, v154
	v_fmac_f32_e32 v147, s78, v154
	v_fmac_f32_e32 v148, s79, v154
	v_fmac_f32_e32 v149, s80, v154
	v_fmac_f32_e32 v150, s81, v154
	v_fmac_f32_e32 v151, s82, v154
	v_fmac_f32_e32 v152, s83, v154
	v_fmac_f32_e32 v153, s84, v154
	v_readlane_b32 s88, v129, 59
	v_readlane_b32 s77, v131, 59
	v_readlane_b32 s78, v133, 59
	v_readlane_b32 s79, v135, 59
	v_readlane_b32 s80, v137, 59
	v_readlane_b32 s81, v139, 59
	v_readlane_b32 s82, v141, 59
	v_readlane_b32 s83, v143, 59
	v_readlane_b32 s84, v145, 59
	v_mul_f32_e32 v154, s88, v123
	v_fmac_f32_e32 v146, s77, v154
	v_fmac_f32_e32 v147, s78, v154
	v_fmac_f32_e32 v148, s79, v154
	v_fmac_f32_e32 v149, s80, v154
	v_fmac_f32_e32 v150, s81, v154
	v_fmac_f32_e32 v151, s82, v154
	v_fmac_f32_e32 v152, s83, v154
	v_fmac_f32_e32 v153, s84, v154
	v_readlane_b32 s88, v129, 60
	v_readlane_b32 s77, v131, 60
	v_readlane_b32 s78, v133, 60
	v_readlane_b32 s79, v135, 60
	v_readlane_b32 s80, v137, 60
	v_readlane_b32 s81, v139, 60
	v_readlane_b32 s82, v141, 60
	v_readlane_b32 s83, v143, 60
	v_readlane_b32 s84, v145, 60
	v_mul_f32_e32 v154, s88, v124
	v_fmac_f32_e32 v146, s77, v154
	v_fmac_f32_e32 v147, s78, v154
	v_fmac_f32_e32 v148, s79, v154
	v_fmac_f32_e32 v149, s80, v154
	v_fmac_f32_e32 v150, s81, v154
	v_fmac_f32_e32 v151, s82, v154
	v_fmac_f32_e32 v152, s83, v154
	v_fmac_f32_e32 v153, s84, v154
	v_readlane_b32 s88, v129, 61
	v_readlane_b32 s77, v131, 61
	v_readlane_b32 s78, v133, 61
	v_readlane_b32 s79, v135, 61
	v_readlane_b32 s80, v137, 61
	v_readlane_b32 s81, v139, 61
	v_readlane_b32 s82, v141, 61
	v_readlane_b32 s83, v143, 61
	v_readlane_b32 s84, v145, 61
	v_mul_f32_e32 v154, s88, v125
	v_fmac_f32_e32 v146, s77, v154
	v_fmac_f32_e32 v147, s78, v154
	v_fmac_f32_e32 v148, s79, v154
	v_fmac_f32_e32 v149, s80, v154
	v_fmac_f32_e32 v150, s81, v154
	v_fmac_f32_e32 v151, s82, v154
	v_fmac_f32_e32 v152, s83, v154
	v_fmac_f32_e32 v153, s84, v154
	v_readlane_b32 s88, v129, 62
	v_readlane_b32 s77, v131, 62
	v_readlane_b32 s78, v133, 62
	v_readlane_b32 s79, v135, 62
	v_readlane_b32 s80, v137, 62
	v_readlane_b32 s81, v139, 62
	v_readlane_b32 s82, v141, 62
	v_readlane_b32 s83, v143, 62
	v_readlane_b32 s84, v145, 62
	v_mul_f32_e32 v154, s88, v126
	v_fmac_f32_e32 v146, s77, v154
	v_fmac_f32_e32 v147, s78, v154
	v_fmac_f32_e32 v148, s79, v154
	v_fmac_f32_e32 v149, s80, v154
	v_fmac_f32_e32 v150, s81, v154
	v_fmac_f32_e32 v151, s82, v154
	v_fmac_f32_e32 v152, s83, v154
	v_fmac_f32_e32 v153, s84, v154
	v_readlane_b32 s88, v129, 63
	v_readlane_b32 s77, v131, 63
	v_readlane_b32 s78, v133, 63
	v_readlane_b32 s79, v135, 63
	v_readlane_b32 s80, v137, 63
	v_readlane_b32 s81, v139, 63
	v_readlane_b32 s82, v141, 63
	v_readlane_b32 s83, v143, 63
	v_readlane_b32 s84, v145, 63
	v_mul_f32_e32 v154, s88, v127
	v_fmac_f32_e32 v146, s77, v154
	v_fmac_f32_e32 v147, s78, v154
	v_fmac_f32_e32 v148, s79, v154
	v_fmac_f32_e32 v149, s80, v154
	v_fmac_f32_e32 v150, s81, v154
	v_fmac_f32_e32 v151, s82, v154
	v_fmac_f32_e32 v152, s83, v154
	v_fmac_f32_e32 v153, s84, v154
	v_cvt_pk_bf16_f32 v72, v146, v147
	v_cvt_pk_bf16_f32 v73, v148, v149
	v_cvt_pk_bf16_f32 v74, v150, v151
	v_cvt_pk_bf16_f32 v75, v152, v153
	s_lshl_b32 s79, s27, 1
	s_add_u32 s86, s18, 0x900000
	s_addc_u32 s87, s19, 0
	s_add_u32 s86, s86, s79
	s_addc_u32 s87, s87, 0
	v_lshlrev_b32_e32 v158, 11, v155
	global_store_dwordx4 v158, v[72:75], s[86:87]
.Ldef_fold_done:
	s_waitcnt vmcnt(0) lgkmcnt(0)
	s_barrier
	s_cmp_lg_u32 s74, 0
	s_cbranch_scc1 .Ldef_pub_done
	v_cmp_eq_u32_e32 vcc, 0, v212
	s_and_saveexec_b64 s[80:81], vcc
	s_cbranch_execz .Ldef_pub_restore
	buffer_wbl2 sc1
	s_waitcnt vmcnt(0)
	v_mov_b32_e32 v0, 0
	v_mov_b32_e32 v1, 1
	global_atomic_add v0, v1, s[18:19] offset:2816
.Ldef_pub_restore:
	s_or_b64 exec, exec, s[80:81]
.Ldef_pub_done:
.Ldef_skip:
	s_cmp_lg_u32 s76, 0
	s_cselect_b64 s[12:13], -1, 0
	s_lshr_b32 s8, s21, 29
	s_add_i32 s8, s20, s8
	s_ashr_i32 s54, s8, 3
	s_lshl_b32 s8, s2, 6
	s_and_b32 s8, s8, 0x1c0
	s_cmp_eq_u32 s76, 0
	v_writelane_b32 v248, s8, 4
	s_cbranch_scc1 .LBB0_360
	s_mov_b64 s[10:11], s[18:19]
	s_and_b64 vcc, exec, s[4:5]
	s_mov_b64 s[14:15], 0
	s_cbranch_vccnz .LBB0_352
	v_mov_b32_e32 v0, v212
	s_nop 0
	v_cmp_eq_u32_e32 vcc, 0, v0
	s_and_b64 s[14:15], vcc, exec

; __device__ __forceinline__ int hw_lane() { int l = (int)__builtin_amdgcn_mbcnt_hi(~0u, __builtin_amdgcn_mbcnt_lo(~0u, 0u)); asm volatile("" : "+v"(l)); return l; }
; #define PG8_LAS __attribute__((address_space(3)))
; #define PG8_STAGE(bufoff, gbase, voff) do { _Pragma("unroll") for (int _i = 0; _i < 2; ++_i) \
;         __builtin_amdgcn_global_load_lds((const unsigned*)((const char*)(gbase) + (voff)[_i]), (PG8_LAS unsigned*)(lds + (bufoff) + ldsw + _i * 8192), 16, 0, 0); } while (0)
;     __host__ __device__ bool next(int i, Unit& u) const {
;         const long L = (long)i * G + c; if (L >= nwg) return false;
;         int wgid = (int)L; { const int q = nwg / NXCD, r = nwg % NXCD, xcd = wgid % NXCD, off = wgid / NXCD; wgid = (xcd < r ? xcd * (q + 1) : r * (q + 1) + (xcd - r) * q) + off; }
;         const int nig = WGM * nN, gid = wgid / nig, fm = gid * WGM, gsz = (nM - fm) < WGM ? (nM - fm) : WGM;
;         u.pm = fm + ((wgid % nig) % gsz); u.pn = (wgid % nig) / gsz; return true;
;     }
; __device__ __forceinline__ unsigned cvt_pk_bf16(float lo, float hi) { unsigned r; asm volatile("v_cvt_pk_bf16_f32 %0, %1, %2" : "=v"(r) : "v"(lo), "v"(hi)); return r; }
; template <class Epi, class Sched, bool ALIGN_EPI = false, bool SP2 = false>
; __device__ __forceinline__ void gemm_phase(PG8_LAS unsigned char* lds, const Gemm g, const Sched& S, const Epi& E, const int wv) {
;     const int wid = wv, lane = hw_lane(), tid = wid * 64 + lane, wr = wid >> 2, wc = wid & 3, fr = lane & 15, fq = lane >> 4;
;     const int K = g.K, nt = K / BK;
;     unsigned voffA[2], voffB[2];
; #pragma unroll
;     for (int i = 0; i < 2; ++i) { int R, C; stage_rc(tid * 16 + i * 8192, R, C); const int Rb = Epi::PERM ? ((R & ~31) + perm32(R & 31)) : R;
;         voffA[i] = (unsigned)(R * K + C) * 2u; voffB[i] = (unsigned)(Rb * K + C) * 2u; }
;     ...
;     const char* cA = (const char*)g.A + (size_t)cur.pm * tstep; const char* cB = (const char*)g.Bt + (size_t)cur.pn * tstep;
;     S.a_ready(cur);
;     if constexpr (SP2) {
;         PG8_STAGE(PG8_SB(0, 0), cB, voffB); PG8_STAGE(PG8_SB(0, 1), cB + hstep, voffB); PG8_STAGE(PG8_SA(0, 0), cA, voffA); PG8_STAGE(PG8_SA(0, 1), cA + hstep, voffA);
.LBB0_499:
	s_cmp_lg_u32 s20, 0x100
	s_cbranch_scc1 .Lrd_skip
	v_mov_b32_e32 v0, 0
.Lrd_poll:
	global_load_dword v1, v0, s[18:19] offset:2816 sc1
	s_waitcnt vmcnt(0)
	v_readfirstlane_b32 s98, v1
	s_cmp_ge_u32 s98, 192
	s_cbranch_scc1 .Lrd_ok
	s_sleep 2
	s_branch .Lrd_poll
.Lrd_ok:
	buffer_inv sc1
	s_waitcnt vmcnt(0)
.Lrd_skip:
	s_mov_b64 s[8:9], s[18:19]
	s_cmpk_lt_i32 s2, 0x200
	s_cselect_b64 s[14:15], -1, 0
	s_waitcnt lgkmcnt(0)
	s_waitcnt lgkmcnt(0)
	s_waitcnt lgkmcnt(0)
	s_waitcnt lgkmcnt(0)
	s_waitcnt lgkmcnt(0)
	s_waitcnt lgkmcnt(0)
	s_waitcnt lgkmcnt(0)
	s_waitcnt lgkmcnt(0)
	s_waitcnt lgkmcnt(0)
	s_waitcnt lgkmcnt(0)
	s_waitcnt lgkmcnt(0)
	s_waitcnt lgkmcnt(0)
	s_waitcnt lgkmcnt(0)
	s_waitcnt lgkmcnt(0)
	s_waitcnt lgkmcnt(0)
	s_waitcnt lgkmcnt(0)
	s_waitcnt lgkmcnt(0)
	s_waitcnt lgkmcnt(0)
	s_waitcnt lgkmcnt(0)
	s_mov_b64 s[24:25], s[16:17]
	v_mov_b32_e32 v9, v212
	s_cmpk_gt_i32 s2, 0x1ff
	s_mul_i32 s60, s68, 0x41
	s_waitcnt lgkmcnt(0)
	s_cbranch_scc1 .LBB0_521
	v_lshl_add_u32 v0, v9, 4, s64
	v_add_u32_e32 v1, 0x2000, v0
	v_ashrrev_i32_e32 v2, 31, v1
	v_lshrrev_b32_e32 v2, 22, v2
	v_add_u32_e32 v2, v1, v2
	v_ashrrev_i32_e32 v8, 10, v2
	v_mul_i32_i24_e32 v2, 0x400, v8
	v_sub_u32_e32 v1, v1, v2
	v_lshrrev_b32_e32 v2, 4, v1
	v_bitop3_b32 v1, v2, v1, 32 bitop3:0x6c
	v_ashrrev_i32_e32 v2, 31, v1
	v_lshrrev_b32_e32 v2, 26, v2
	v_add_u32_e32 v2, v1, v2
	v_ashrrev_i32_e32 v10, 6, v2
	v_lshlrev_b32_e32 v3, 3, v8
	v_and_b32_e32 v2, 0xffc0, v2
	v_and_b32_e32 v3, -16, v3
	v_sub_u32_e32 v1, v1, v2
	v_add_u32_e32 v3, v10, v3
	v_lshrrev_b16_e32 v2, 7, v1
	v_and_b32_e32 v4, 3, v10
	s_mov_b32 s10, 0x1fffe0
	v_lshrrev_b32_e32 v5, 2, v3
	v_lshlrev_b32_e32 v6, 1, v3
	v_and_b32_e32 v2, 1, v2
	v_and_or_b32 v4, v3, s10, v4
	v_and_b32_e32 v5, 4, v5
	v_and_b32_e32 v6, 24, v6
	v_add_u16_e32 v1, v1, v2
	v_mov_b32_e32 v2, 1
	v_or3_b32 v4, v4, v5, v6
	v_lshlrev_b32_e32 v5, 5, v8
	v_ashrrev_i16_sdwa v1, v2, sext(v1) dst_sel:DWORD dst_unused:UNUSED_PAD src0_sel:DWORD src1_sel:BYTE_0
	v_and_b32_e32 v5, 32, v5
	v_bfe_i32 v11, v1, 0, 16
	v_add_lshl_u32 v1, v5, v11, 1
	v_lshl_add_u32 v168, v4, 11, v1
	v_lshl_add_u32 v170, v3, 11, v1
	v_ashrrev_i32_e32 v1, 31, v0
	v_lshrrev_b32_e32 v1, 22, v1
	v_add_u32_e32 v1, v0, v1
	v_ashrrev_i32_e32 v12, 10, v1
	v_mul_i32_i24_e32 v1, 0x400, v12
	v_sub_u32_e32 v0, v0, v1
	v_lshrrev_b32_e32 v1, 4, v0
	v_bitop3_b32 v0, v1, v0, 32 bitop3:0x6c
	v_ashrrev_i32_e32 v1, 31, v0
	s_add_u32 s52, s8, 0x900000
	v_lshrrev_b32_e32 v1, 26, v1
	s_addc_u32 s53, s9, 0
	v_add_u32_e32 v1, v0, v1
	v_lshlrev_b32_e32 v3, 3, v12
	s_add_u32 s63, s8, 0x3c00000
	v_ashrrev_i32_e32 v13, 6, v1
	v_and_b32_e32 v3, -16, v3
	s_addc_u32 s74, s9, 0
	v_add_u32_e32 v3, v13, v3
	v_and_b32_e32 v4, 3, v13
	s_lshl_b32 s24, s68, 6
	v_and_or_b32 v4, v3, s10, v4
	s_and_b64 s[10:11], s[94:95], exec
	s_cselect_b32 s10, s60, s24
	s_add_i32 s10, s10, s67
	s_ashr_i32 s11, s10, 31
	s_lshr_b32 s11, s11, 27
	s_add_i32 s11, s10, s11
	s_ashr_i32 s24, s11, 5
	s_and_b32 s11, s11, 0xffe0
	s_sub_i32 s10, s10, s11
	s_bfe_i32 s11, s10, 0x80000
	s_bfe_u32 s11, s11, 0x3000c
	s_add_i32 s11, s10, s11
	s_bfe_i32 s25, s11, 0x80000
	s_and_b32 s11, s11, 0xf8
	s_sub_i32 s10, s10, s11
	s_lshl_b32 s24, s24, 3
	s_sext_i32_i16 s25, s25
	s_sext_i32_i8 s10, s10
	v_lshrrev_b32_e32 v5, 2, v3
	v_lshlrev_b32_e32 v6, 1, v3
	v_and_b32_e32 v1, 0xc0, v1
	s_lshr_b32 s30, s25, 3
	s_add_i32 s44, s24, s10
	v_and_b32_e32 v5, 4, v5
	v_and_b32_e32 v6, 24, v6
	v_sub_u32_e32 v0, v0, v1
	s_ashr_i32 s45, s44, 31
	s_bfe_i64 s[24:25], s[30:31], 0x100000
	v_or3_b32 v4, v4, v5, v6
	v_lshlrev_b32_e32 v5, 5, v12
	v_ashrrev_i16_sdwa v0, v2, sext(v0) dst_sel:DWORD dst_unused:UNUSED_PAD src0_sel:DWORD src1_sel:BYTE_0
	s_lshl_b64 s[10:11], s[44:45], 19
	s_lshl_b64 s[24:25], s[24:25], 19
	v_and_b32_e32 v5, 32, v5
	v_bfe_i32 v14, v0, 0, 16
	s_add_u32 s46, s52, s24
	v_add_lshl_u32 v0, v5, v14, 1
	s_addc_u32 s47, s53, s25
	s_add_i32 s75, s64, 0
	v_lshl_add_u32 v172, v4, 11, v0
	s_add_i32 m0, s75, 0x10000
	v_lshl_add_u32 v174, v3, 11, v0
	global_load_lds_dwordx4 v172, s[46:47]
	s_add_i32 m0, s75, 0x12000
	s_add_u32 s24, s46, 0x40000
	global_load_lds_dwordx4 v168, s[46:47]
	s_addc_u32 s25, s47, 0
	s_add_i32 m0, s75, 0x14000
	v_mov_b32_e32 v173, 0
	global_load_lds_dwordx4 v172, s[24:25]
	s_add_i32 m0, s75, 0x16000
	s_add_u32 s42, s63, s10
	s_addc_u32 s43, s74, s11
	s_add_i32 s76, s75, 0x2000
	global_load_lds_dwordx4 v168, s[24:25]
	s_mov_b32 m0, s75
	s_add_u32 s10, s42, 0x40000
	global_load_lds_dwordx4 v174, s[42:43]
	s_mov_b32 m0, s76
	s_addc_u32 s11, s43, 0
	s_add_i32 s77, s75, 0x4000
	global_load_lds_dwordx4 v170, s[42:43]
	s_mov_b32 m0, s77
	s_add_i32 s78, s75, 0x6000
	global_load_lds_dwordx4 v174, s[10:11]
	s_mov_b32 m0, s78
	v_mov_b32_e32 v169, v173
	global_load_lds_dwordx4 v170, s[10:11]
	v_mov_b32_e32 v175, v173
	v_mov_b32_e32 v171, v173
	v_lshl_add_u64 v[6:7], s[46:47], 0, v[172:173]
	v_lshl_add_u64 v[4:5], s[46:47], 0, v[168:169]
	v_lshl_add_u64 v[2:3], s[42:43], 0, v[174:175]
	s_and_b64 vcc, exec, s[6:7]
	v_lshl_add_u64 v[0:1], s[42:43], 0, v[170:171]
	s_cbranch_vccnz .LBB0_502
	s_barrier
